# register epilogues (transposed MFMA, cvt_pk, permlane16_swap) for kind 1, 10 and GLU GEMMs
# speedup vs baseline: 1.0230x; 1.0175x over previous
; __device__ __forceinline__ float siluf_(float x) { return x * frcp(1.0f + fexp(-x)); }
; #define SCHED __builtin_amdgcn_sched_barrier(0)
; template <int EPI>
; __device__ __forceinline__ void gemm_tile(const GemmArgs& g, int brow, int bcol, int parity, bool first, bool nvalid, int nbrow, int nbcol) {
;     ...
;   } else if constexpr (EPI == EPI_GLU) {
;     const int tn = bcol >> 8;
;     _Pragma("unroll") for (int ai = 0; ai < 2; ++ai) {
;       SCHED;
;       _Pragma("unroll") for (int m = 0; m < 4; ++m) _Pragma("unroll") for (int j = 0; j < 4; ++j) {
;         const float rs = rstd_s[lrow0 + ai * HALF + m * 16 + fq * 4 + j];
;         _Pragma("unroll") for (int n = 0; n < 2; ++n) {
;           const float gg = acc[ai][0][m][n][j] * rs, uu = acc[ai][1][m][n][j] * rs;
;           W_WRITE(m, n, j, siluf_(gg) * uu);
;         }
;       }
;       bfu* dst = g.outb + (long)(wrow0 + ai * HALF) * g.ldo + tn * 128 + (wcol0 - bcol);
;       W_STORE_BF16(dst, g.ldo);
;     }
.LBB0_152:
	v_mbcnt_lo_u32_b32 v130, -1, 0
	v_mbcnt_hi_u32_b32 v130, -1, v130
	s_add_i32 s24, s24, 1
	s_and_b32 s2, s33, 0x100
	s_add_i32 s2, s2, s14
	v_and_b32_e32 v131, 15, v130
	v_lshrrev_b32_e32 v132, 4, v130
	v_lshl_add_u32 v133, v131, 2, s2
	ds_read_b32 v138, v133
	ds_read_b32 v139, v133 offset:64
	ds_read_b32 v140, v133 offset:128
	ds_read_b32 v141, v133 offset:192
	ds_read_b32 v142, v133 offset:512
	ds_read_b32 v143, v133 offset:576
	ds_read_b32 v144, v133 offset:640
	ds_read_b32 v145, v133 offset:704
	v_lshlrev_b32_e32 v134, 4, v132
	v_lshlrev_b32_e32 v135, 2, v132
	v_and_b32_e32 v134, 16, v134
	v_and_b32_e32 v135, 8, v135
	s_lshl_b32 s3, s34, 4
	s_and_b32 s3, s3, 0xffffff80
	s_lshr_b32 s12, s33, 1
	s_and_b32 s12, s12, 0x60
	s_add_i32 s3, s3, s12
	v_or_b32_e32 v134, v134, v135
	v_add_lshl_u32 v134, v134, s3, 1
	v_mov_b32_e32 v135, 0
	s_lshr_b32 s12, s33, 2
	s_and_b32 s12, s12, 64
	s_add_i32 s12, s12, s38
	v_add_u32_e32 v136, s12, v131
	s_movk_i32 s3, 0x1600
	v_mad_u64_u32 v[134:135], vcc, v136, s3, v[134:135]
	v_lshl_add_u64 v[134:135], v[134:135], 0, s[16:17]
	s_mov_b64 s[12:13], 0x16000
	s_mov_b64 s[14:15], 0x6e000
	v_mov_b32_e32 v146, 0xbfb8aa3b
	v_mov_b32_e32 v147, 1.0
	s_waitcnt lgkmcnt(0)
	v_pk_mul_f32 v[122:123], v[122:123], v[138:139] op_sel_hi:[1,0]
	v_pk_mul_f32 v[124:125], v[124:125], v[138:139] op_sel_hi:[1,0]
	v_pk_mul_f32 v[114:115], v[114:115], v[138:139] op_sel_hi:[1,0]
	v_pk_mul_f32 v[116:117], v[116:117], v[138:139] op_sel_hi:[1,0]
	v_pk_mul_f32 v[126:127], v[126:127], v[138:139] op_sel_hi:[1,0]
	v_pk_mul_f32 v[128:129], v[128:129], v[138:139] op_sel_hi:[1,0]
	v_pk_mul_f32 v[118:119], v[118:119], v[138:139] op_sel_hi:[1,0]
	v_pk_mul_f32 v[120:121], v[120:121], v[138:139] op_sel_hi:[1,0]
	v_pk_mul_f32 v[148:149], v[122:123], v[146:147] op_sel_hi:[1,0]
	v_pk_mul_f32 v[150:151], v[124:125], v[146:147] op_sel_hi:[1,0]
	v_pk_mul_f32 v[152:153], v[114:115], v[146:147] op_sel_hi:[1,0]
	v_pk_mul_f32 v[154:155], v[116:117], v[146:147] op_sel_hi:[1,0]
	v_exp_f32_e32 v148, v148
	v_exp_f32_e32 v149, v149
	v_exp_f32_e32 v150, v150
	v_exp_f32_e32 v151, v151
	v_exp_f32_e32 v152, v152
	v_exp_f32_e32 v153, v153
	v_exp_f32_e32 v154, v154
	v_exp_f32_e32 v155, v155
	v_pk_add_f32 v[148:149], v[148:149], v[146:147] op_sel:[0,1] op_sel_hi:[1,1]
	v_pk_add_f32 v[150:151], v[150:151], v[146:147] op_sel:[0,1] op_sel_hi:[1,1]
	v_pk_add_f32 v[152:153], v[152:153], v[146:147] op_sel:[0,1] op_sel_hi:[1,1]
	v_pk_add_f32 v[154:155], v[154:155], v[146:147] op_sel:[0,1] op_sel_hi:[1,1]
	v_rcp_f32_e32 v148, v148
	v_rcp_f32_e32 v149, v149
	v_rcp_f32_e32 v150, v150
	v_rcp_f32_e32 v151, v151
	v_rcp_f32_e32 v152, v152
	v_rcp_f32_e32 v153, v153
	v_rcp_f32_e32 v154, v154
	v_rcp_f32_e32 v155, v155
	v_pk_mul_f32 v[122:123], v[122:123], v[148:149]
	v_pk_mul_f32 v[124:125], v[124:125], v[150:151]
	v_pk_mul_f32 v[114:115], v[114:115], v[152:153]
	v_pk_mul_f32 v[116:117], v[116:117], v[154:155]
	v_pk_mul_f32 v[122:123], v[126:127], v[122:123]
	v_pk_mul_f32 v[124:125], v[128:129], v[124:125]
	v_pk_mul_f32 v[114:115], v[118:119], v[114:115]
	v_pk_mul_f32 v[116:117], v[120:121], v[116:117]
	v_cvt_pk_bf16_f32 v156, v122, v123
	v_cvt_pk_bf16_f32 v157, v124, v125
	v_cvt_pk_bf16_f32 v158, v114, v115
	v_cvt_pk_bf16_f32 v159, v116, v117
	v_pk_mul_f32 v[106:107], v[106:107], v[138:139] op_sel:[0,1] op_sel_hi:[1,1]
	v_pk_mul_f32 v[108:109], v[108:109], v[138:139] op_sel:[0,1] op_sel_hi:[1,1]
	v_pk_mul_f32 v[98:99], v[98:99], v[138:139] op_sel:[0,1] op_sel_hi:[1,1]
	v_pk_mul_f32 v[100:101], v[100:101], v[138:139] op_sel:[0,1] op_sel_hi:[1,1]
	v_pk_mul_f32 v[110:111], v[110:111], v[138:139] op_sel:[0,1] op_sel_hi:[1,1]
	v_pk_mul_f32 v[112:113], v[112:113], v[138:139] op_sel:[0,1] op_sel_hi:[1,1]
	v_pk_mul_f32 v[102:103], v[102:103], v[138:139] op_sel:[0,1] op_sel_hi:[1,1]
	v_pk_mul_f32 v[104:105], v[104:105], v[138:139] op_sel:[0,1] op_sel_hi:[1,1]
	v_permlane16_swap_b32_e32 v156, v158
	v_permlane16_swap_b32_e32 v157, v159
	global_store_dwordx4 v[134:135], v[156:159], off
	v_lshl_add_u64 v[134:135], v[134:135], 0, s[12:13]
	v_pk_mul_f32 v[148:149], v[106:107], v[146:147] op_sel_hi:[1,0]
	v_pk_mul_f32 v[150:151], v[108:109], v[146:147] op_sel_hi:[1,0]
	v_pk_mul_f32 v[152:153], v[98:99], v[146:147] op_sel_hi:[1,0]
	v_pk_mul_f32 v[154:155], v[100:101], v[146:147] op_sel_hi:[1,0]
	v_exp_f32_e32 v148, v148
	v_exp_f32_e32 v149, v149
	v_exp_f32_e32 v150, v150
	v_exp_f32_e32 v151, v151
	v_exp_f32_e32 v152, v152
	v_exp_f32_e32 v153, v153
	v_exp_f32_e32 v154, v154
	v_exp_f32_e32 v155, v155
	v_pk_add_f32 v[148:149], v[148:149], v[146:147] op_sel:[0,1] op_sel_hi:[1,1]
	v_pk_add_f32 v[150:151], v[150:151], v[146:147] op_sel:[0,1] op_sel_hi:[1,1]
	v_pk_add_f32 v[152:153], v[152:153], v[146:147] op_sel:[0,1] op_sel_hi:[1,1]
	v_pk_add_f32 v[154:155], v[154:155], v[146:147] op_sel:[0,1] op_sel_hi:[1,1]
	v_rcp_f32_e32 v148, v148
	v_rcp_f32_e32 v149, v149
	v_rcp_f32_e32 v150, v150
	v_rcp_f32_e32 v151, v151
	v_rcp_f32_e32 v152, v152
	v_rcp_f32_e32 v153, v153
	v_rcp_f32_e32 v154, v154
	v_rcp_f32_e32 v155, v155
	v_pk_mul_f32 v[106:107], v[106:107], v[148:149]
	v_pk_mul_f32 v[108:109], v[108:109], v[150:151]
	v_pk_mul_f32 v[98:99], v[98:99], v[152:153]
	v_pk_mul_f32 v[100:101], v[100:101], v[154:155]
	v_pk_mul_f32 v[106:107], v[110:111], v[106:107]
	v_pk_mul_f32 v[108:109], v[112:113], v[108:109]
	v_pk_mul_f32 v[98:99], v[102:103], v[98:99]
	v_pk_mul_f32 v[100:101], v[104:105], v[100:101]
	v_cvt_pk_bf16_f32 v160, v106, v107
	v_cvt_pk_bf16_f32 v161, v108, v109
	v_cvt_pk_bf16_f32 v162, v98, v99
	v_cvt_pk_bf16_f32 v163, v100, v101
	v_pk_mul_f32 v[90:91], v[90:91], v[140:141] op_sel_hi:[1,0]
; __device__ __forceinline__ float siluf_(float x) { return x * frcp(1.0f + fexp(-x)); }
; #define SCHED __builtin_amdgcn_sched_barrier(0)
; template <int EPI>
; __device__ __forceinline__ void gemm_tile(const GemmArgs& g, int brow, int bcol, int parity, bool first, bool nvalid, int nbrow, int nbcol) {
;     ...
;     _Pragma("unroll") for (int ai = 0; ai < 2; ++ai) {
;       SCHED;
;       _Pragma("unroll") for (int m = 0; m < 4; ++m) _Pragma("unroll") for (int j = 0; j < 4; ++j) {
;         const float rs = rstd_s[lrow0 + ai * HALF + m * 16 + fq * 4 + j];
;         _Pragma("unroll") for (int n = 0; n < 2; ++n) {
;           const float gg = acc[ai][0][m][n][j] * rs, uu = acc[ai][1][m][n][j] * rs;
;           W_WRITE(m, n, j, siluf_(gg) * uu);
;         }
;       }
;       bfu* dst = g.outb + (long)(wrow0 + ai * HALF) * g.ldo + tn * 128 + (wcol0 - bcol);
;       W_STORE_BF16(dst, g.ldo);
;     }
	v_pk_mul_f32 v[92:93], v[92:93], v[140:141] op_sel_hi:[1,0]
	v_pk_mul_f32 v[82:83], v[82:83], v[140:141] op_sel_hi:[1,0]
	v_pk_mul_f32 v[84:85], v[84:85], v[140:141] op_sel_hi:[1,0]
	v_pk_mul_f32 v[94:95], v[94:95], v[140:141] op_sel_hi:[1,0]
	v_pk_mul_f32 v[96:97], v[96:97], v[140:141] op_sel_hi:[1,0]
	v_pk_mul_f32 v[86:87], v[86:87], v[140:141] op_sel_hi:[1,0]
	v_pk_mul_f32 v[88:89], v[88:89], v[140:141] op_sel_hi:[1,0]
	v_permlane16_swap_b32_e32 v160, v162
	v_permlane16_swap_b32_e32 v161, v163
	global_store_dwordx4 v[134:135], v[160:163], off
	v_lshl_add_u64 v[134:135], v[134:135], 0, s[12:13]
	v_pk_mul_f32 v[148:149], v[90:91], v[146:147] op_sel_hi:[1,0]
	v_pk_mul_f32 v[150:151], v[92:93], v[146:147] op_sel_hi:[1,0]
	v_pk_mul_f32 v[152:153], v[82:83], v[146:147] op_sel_hi:[1,0]
	v_pk_mul_f32 v[154:155], v[84:85], v[146:147] op_sel_hi:[1,0]
	v_exp_f32_e32 v148, v148
	v_exp_f32_e32 v149, v149
	v_exp_f32_e32 v150, v150
	v_exp_f32_e32 v151, v151
	v_exp_f32_e32 v152, v152
	v_exp_f32_e32 v153, v153
	v_exp_f32_e32 v154, v154
	v_exp_f32_e32 v155, v155
	v_pk_add_f32 v[148:149], v[148:149], v[146:147] op_sel:[0,1] op_sel_hi:[1,1]
	v_pk_add_f32 v[150:151], v[150:151], v[146:147] op_sel:[0,1] op_sel_hi:[1,1]
	v_pk_add_f32 v[152:153], v[152:153], v[146:147] op_sel:[0,1] op_sel_hi:[1,1]
	v_pk_add_f32 v[154:155], v[154:155], v[146:147] op_sel:[0,1] op_sel_hi:[1,1]
	v_rcp_f32_e32 v148, v148
	v_rcp_f32_e32 v149, v149
	v_rcp_f32_e32 v150, v150
	v_rcp_f32_e32 v151, v151
	v_rcp_f32_e32 v152, v152
	v_rcp_f32_e32 v153, v153
	v_rcp_f32_e32 v154, v154
	v_rcp_f32_e32 v155, v155
	v_pk_mul_f32 v[90:91], v[90:91], v[148:149]
	v_pk_mul_f32 v[92:93], v[92:93], v[150:151]
	v_pk_mul_f32 v[82:83], v[82:83], v[152:153]
	v_pk_mul_f32 v[84:85], v[84:85], v[154:155]
	v_pk_mul_f32 v[90:91], v[94:95], v[90:91]
	v_pk_mul_f32 v[92:93], v[96:97], v[92:93]
	v_pk_mul_f32 v[82:83], v[86:87], v[82:83]
	v_pk_mul_f32 v[84:85], v[88:89], v[84:85]
	v_cvt_pk_bf16_f32 v156, v90, v91
	v_cvt_pk_bf16_f32 v157, v92, v93
	v_cvt_pk_bf16_f32 v158, v82, v83
	v_cvt_pk_bf16_f32 v159, v84, v85
	v_pk_mul_f32 v[70:71], v[70:71], v[140:141] op_sel:[0,1] op_sel_hi:[1,1]
	v_pk_mul_f32 v[72:73], v[72:73], v[140:141] op_sel:[0,1] op_sel_hi:[1,1]
	v_pk_mul_f32 v[66:67], v[66:67], v[140:141] op_sel:[0,1] op_sel_hi:[1,1]
	v_pk_mul_f32 v[68:69], v[68:69], v[140:141] op_sel:[0,1] op_sel_hi:[1,1]
	v_pk_mul_f32 v[78:79], v[78:79], v[140:141] op_sel:[0,1] op_sel_hi:[1,1]
	v_pk_mul_f32 v[80:81], v[80:81], v[140:141] op_sel:[0,1] op_sel_hi:[1,1]
	v_pk_mul_f32 v[74:75], v[74:75], v[140:141] op_sel:[0,1] op_sel_hi:[1,1]
	v_pk_mul_f32 v[76:77], v[76:77], v[140:141] op_sel:[0,1] op_sel_hi:[1,1]
	v_permlane16_swap_b32_e32 v156, v158
	v_permlane16_swap_b32_e32 v157, v159
	global_store_dwordx4 v[134:135], v[156:159], off
	v_lshl_add_u64 v[134:135], v[134:135], 0, s[12:13]
	v_pk_mul_f32 v[148:149], v[70:71], v[146:147] op_sel_hi:[1,0]
	v_pk_mul_f32 v[150:151], v[72:73], v[146:147] op_sel_hi:[1,0]
	v_pk_mul_f32 v[152:153], v[66:67], v[146:147] op_sel_hi:[1,0]
	v_pk_mul_f32 v[154:155], v[68:69], v[146:147] op_sel_hi:[1,0]
	v_exp_f32_e32 v148, v148
	v_exp_f32_e32 v149, v149
	v_exp_f32_e32 v150, v150
	v_exp_f32_e32 v151, v151
	v_exp_f32_e32 v152, v152
	v_exp_f32_e32 v153, v153
	v_exp_f32_e32 v154, v154
	v_exp_f32_e32 v155, v155
	v_pk_add_f32 v[148:149], v[148:149], v[146:147] op_sel:[0,1] op_sel_hi:[1,1]
	v_pk_add_f32 v[150:151], v[150:151], v[146:147] op_sel:[0,1] op_sel_hi:[1,1]
	v_pk_add_f32 v[152:153], v[152:153], v[146:147] op_sel:[0,1] op_sel_hi:[1,1]
	v_pk_add_f32 v[154:155], v[154:155], v[146:147] op_sel:[0,1] op_sel_hi:[1,1]
	v_rcp_f32_e32 v148, v148
	v_rcp_f32_e32 v149, v149
	v_rcp_f32_e32 v150, v150
	v_rcp_f32_e32 v151, v151
	v_rcp_f32_e32 v152, v152
	v_rcp_f32_e32 v153, v153
	v_rcp_f32_e32 v154, v154
	v_rcp_f32_e32 v155, v155
	v_pk_mul_f32 v[70:71], v[70:71], v[148:149]
	v_pk_mul_f32 v[72:73], v[72:73], v[150:151]
	v_pk_mul_f32 v[66:67], v[66:67], v[152:153]
	v_pk_mul_f32 v[68:69], v[68:69], v[154:155]
	v_pk_mul_f32 v[70:71], v[78:79], v[70:71]
	v_pk_mul_f32 v[72:73], v[80:81], v[72:73]
	v_pk_mul_f32 v[66:67], v[74:75], v[66:67]
	v_pk_mul_f32 v[68:69], v[76:77], v[68:69]
	v_cvt_pk_bf16_f32 v160, v70, v71
	v_cvt_pk_bf16_f32 v161, v72, v73
	v_cvt_pk_bf16_f32 v162, v66, v67
	v_cvt_pk_bf16_f32 v163, v68, v69
	v_pk_mul_f32 v[58:59], v[58:59], v[142:143] op_sel_hi:[1,0]
	v_pk_mul_f32 v[60:61], v[60:61], v[142:143] op_sel_hi:[1,0]
	v_pk_mul_f32 v[50:51], v[50:51], v[142:143] op_sel_hi:[1,0]
	v_pk_mul_f32 v[52:53], v[52:53], v[142:143] op_sel_hi:[1,0]
	v_pk_mul_f32 v[62:63], v[62:63], v[142:143] op_sel_hi:[1,0]
	v_pk_mul_f32 v[64:65], v[64:65], v[142:143] op_sel_hi:[1,0]
	v_pk_mul_f32 v[54:55], v[54:55], v[142:143] op_sel_hi:[1,0]
	v_pk_mul_f32 v[56:57], v[56:57], v[142:143] op_sel_hi:[1,0]
	v_permlane16_swap_b32_e32 v160, v162
	v_permlane16_swap_b32_e32 v161, v163
	global_store_dwordx4 v[134:135], v[160:163], off
	v_lshl_add_u64 v[134:135], v[134:135], 0, s[14:15]
	v_pk_mul_f32 v[148:149], v[58:59], v[146:147] op_sel_hi:[1,0]
	v_pk_mul_f32 v[150:151], v[60:61], v[146:147] op_sel_hi:[1,0]
	v_pk_mul_f32 v[152:153], v[50:51], v[146:147] op_sel_hi:[1,0]
	v_pk_mul_f32 v[154:155], v[52:53], v[146:147] op_sel_hi:[1,0]
	v_exp_f32_e32 v148, v148
	v_exp_f32_e32 v149, v149
	v_exp_f32_e32 v150, v150
	v_exp_f32_e32 v151, v151
	v_exp_f32_e32 v152, v152
	v_exp_f32_e32 v153, v153
	v_exp_f32_e32 v154, v154
	v_exp_f32_e32 v155, v155
	v_pk_add_f32 v[148:149], v[148:149], v[146:147] op_sel:[0,1] op_sel_hi:[1,1]
	v_pk_add_f32 v[150:151], v[150:151], v[146:147] op_sel:[0,1] op_sel_hi:[1,1]
	v_pk_add_f32 v[152:153], v[152:153], v[146:147] op_sel:[0,1] op_sel_hi:[1,1]
; __device__ __forceinline__ float siluf_(float x) { return x * frcp(1.0f + fexp(-x)); }
; #define SCHED __builtin_amdgcn_sched_barrier(0)
; template <int EPI>
; __device__ __forceinline__ void gemm_tile(const GemmArgs& g, int brow, int bcol, int parity, bool first, bool nvalid, int nbrow, int nbcol) {
;     ...
;     _Pragma("unroll") for (int ai = 0; ai < 2; ++ai) {
;       SCHED;
;       _Pragma("unroll") for (int m = 0; m < 4; ++m) _Pragma("unroll") for (int j = 0; j < 4; ++j) {
;         const float rs = rstd_s[lrow0 + ai * HALF + m * 16 + fq * 4 + j];
;         _Pragma("unroll") for (int n = 0; n < 2; ++n) {
;           const float gg = acc[ai][0][m][n][j] * rs, uu = acc[ai][1][m][n][j] * rs;
;           W_WRITE(m, n, j, siluf_(gg) * uu);
;         }
;       }
;       bfu* dst = g.outb + (long)(wrow0 + ai * HALF) * g.ldo + tn * 128 + (wcol0 - bcol);
;       W_STORE_BF16(dst, g.ldo);
;     }
	v_pk_add_f32 v[154:155], v[154:155], v[146:147] op_sel:[0,1] op_sel_hi:[1,1]
	v_rcp_f32_e32 v148, v148
	v_rcp_f32_e32 v149, v149
	v_rcp_f32_e32 v150, v150
	v_rcp_f32_e32 v151, v151
	v_rcp_f32_e32 v152, v152
	v_rcp_f32_e32 v153, v153
	v_rcp_f32_e32 v154, v154
	v_rcp_f32_e32 v155, v155
	v_pk_mul_f32 v[58:59], v[58:59], v[148:149]
	v_pk_mul_f32 v[60:61], v[60:61], v[150:151]
	v_pk_mul_f32 v[50:51], v[50:51], v[152:153]
	v_pk_mul_f32 v[52:53], v[52:53], v[154:155]
	v_pk_mul_f32 v[58:59], v[62:63], v[58:59]
	v_pk_mul_f32 v[60:61], v[64:65], v[60:61]
	v_pk_mul_f32 v[50:51], v[54:55], v[50:51]
	v_pk_mul_f32 v[52:53], v[56:57], v[52:53]
	v_cvt_pk_bf16_f32 v156, v58, v59
	v_cvt_pk_bf16_f32 v157, v60, v61
	v_cvt_pk_bf16_f32 v158, v50, v51
	v_cvt_pk_bf16_f32 v159, v52, v53
	v_pk_mul_f32 v[42:43], v[42:43], v[142:143] op_sel:[0,1] op_sel_hi:[1,1]
	v_pk_mul_f32 v[44:45], v[44:45], v[142:143] op_sel:[0,1] op_sel_hi:[1,1]
	v_pk_mul_f32 v[34:35], v[34:35], v[142:143] op_sel:[0,1] op_sel_hi:[1,1]
	v_pk_mul_f32 v[36:37], v[36:37], v[142:143] op_sel:[0,1] op_sel_hi:[1,1]
	v_pk_mul_f32 v[46:47], v[46:47], v[142:143] op_sel:[0,1] op_sel_hi:[1,1]
	v_pk_mul_f32 v[48:49], v[48:49], v[142:143] op_sel:[0,1] op_sel_hi:[1,1]
	v_pk_mul_f32 v[38:39], v[38:39], v[142:143] op_sel:[0,1] op_sel_hi:[1,1]
	v_pk_mul_f32 v[40:41], v[40:41], v[142:143] op_sel:[0,1] op_sel_hi:[1,1]
	v_permlane16_swap_b32_e32 v156, v158
	v_permlane16_swap_b32_e32 v157, v159
	global_store_dwordx4 v[134:135], v[156:159], off
	v_lshl_add_u64 v[134:135], v[134:135], 0, s[12:13]
	v_pk_mul_f32 v[148:149], v[42:43], v[146:147] op_sel_hi:[1,0]
	v_pk_mul_f32 v[150:151], v[44:45], v[146:147] op_sel_hi:[1,0]
	v_pk_mul_f32 v[152:153], v[34:35], v[146:147] op_sel_hi:[1,0]
	v_pk_mul_f32 v[154:155], v[36:37], v[146:147] op_sel_hi:[1,0]
	v_exp_f32_e32 v148, v148
	v_exp_f32_e32 v149, v149
	v_exp_f32_e32 v150, v150
	v_exp_f32_e32 v151, v151
	v_exp_f32_e32 v152, v152
	v_exp_f32_e32 v153, v153
	v_exp_f32_e32 v154, v154
	v_exp_f32_e32 v155, v155
	v_pk_add_f32 v[148:149], v[148:149], v[146:147] op_sel:[0,1] op_sel_hi:[1,1]
	v_pk_add_f32 v[150:151], v[150:151], v[146:147] op_sel:[0,1] op_sel_hi:[1,1]
	v_pk_add_f32 v[152:153], v[152:153], v[146:147] op_sel:[0,1] op_sel_hi:[1,1]
	v_pk_add_f32 v[154:155], v[154:155], v[146:147] op_sel:[0,1] op_sel_hi:[1,1]
	v_rcp_f32_e32 v148, v148
	v_rcp_f32_e32 v149, v149
	v_rcp_f32_e32 v150, v150
	v_rcp_f32_e32 v151, v151
	v_rcp_f32_e32 v152, v152
	v_rcp_f32_e32 v153, v153
	v_rcp_f32_e32 v154, v154
	v_rcp_f32_e32 v155, v155
	v_pk_mul_f32 v[42:43], v[42:43], v[148:149]
	v_pk_mul_f32 v[44:45], v[44:45], v[150:151]
	v_pk_mul_f32 v[34:35], v[34:35], v[152:153]
	v_pk_mul_f32 v[36:37], v[36:37], v[154:155]
	v_pk_mul_f32 v[42:43], v[46:47], v[42:43]
	v_pk_mul_f32 v[44:45], v[48:49], v[44:45]
	v_pk_mul_f32 v[34:35], v[38:39], v[34:35]
	v_pk_mul_f32 v[36:37], v[40:41], v[36:37]
	v_cvt_pk_bf16_f32 v160, v42, v43
	v_cvt_pk_bf16_f32 v161, v44, v45
	v_cvt_pk_bf16_f32 v162, v34, v35
	v_cvt_pk_bf16_f32 v163, v36, v37
	v_pk_mul_f32 v[26:27], v[26:27], v[144:145] op_sel_hi:[1,0]
	v_pk_mul_f32 v[28:29], v[28:29], v[144:145] op_sel_hi:[1,0]
	v_pk_mul_f32 v[18:19], v[18:19], v[144:145] op_sel_hi:[1,0]
	v_pk_mul_f32 v[20:21], v[20:21], v[144:145] op_sel_hi:[1,0]
	v_pk_mul_f32 v[30:31], v[30:31], v[144:145] op_sel_hi:[1,0]
	v_pk_mul_f32 v[32:33], v[32:33], v[144:145] op_sel_hi:[1,0]
	v_pk_mul_f32 v[22:23], v[22:23], v[144:145] op_sel_hi:[1,0]
	v_pk_mul_f32 v[24:25], v[24:25], v[144:145] op_sel_hi:[1,0]
	v_permlane16_swap_b32_e32 v160, v162
	v_permlane16_swap_b32_e32 v161, v163
	global_store_dwordx4 v[134:135], v[160:163], off
	v_lshl_add_u64 v[134:135], v[134:135], 0, s[12:13]
	v_pk_mul_f32 v[148:149], v[26:27], v[146:147] op_sel_hi:[1,0]
; __device__ __forceinline__ float siluf_(float x) { return x * frcp(1.0f + fexp(-x)); }
; #define SCHED __builtin_amdgcn_sched_barrier(0)
; template <int EPI>
; __device__ __forceinline__ void gemm_tile(const GemmArgs& g, int brow, int bcol, int parity, bool first, bool nvalid, int nbrow, int nbcol) {
;     ...
;     _Pragma("unroll") for (int ai = 0; ai < 2; ++ai) {
;       SCHED;
;       _Pragma("unroll") for (int m = 0; m < 4; ++m) _Pragma("unroll") for (int j = 0; j < 4; ++j) {
;         const float rs = rstd_s[lrow0 + ai * HALF + m * 16 + fq * 4 + j];
;         _Pragma("unroll") for (int n = 0; n < 2; ++n) {
;           const float gg = acc[ai][0][m][n][j] * rs, uu = acc[ai][1][m][n][j] * rs;
;           W_WRITE(m, n, j, siluf_(gg) * uu);
;         }
;       }
;       bfu* dst = g.outb + (long)(wrow0 + ai * HALF) * g.ldo + tn * 128 + (wcol0 - bcol);
;       W_STORE_BF16(dst, g.ldo);
;     }
	v_pk_mul_f32 v[150:151], v[28:29], v[146:147] op_sel_hi:[1,0]
	v_pk_mul_f32 v[152:153], v[18:19], v[146:147] op_sel_hi:[1,0]
	v_pk_mul_f32 v[154:155], v[20:21], v[146:147] op_sel_hi:[1,0]
	v_exp_f32_e32 v148, v148
	v_exp_f32_e32 v149, v149
	v_exp_f32_e32 v150, v150
	v_exp_f32_e32 v151, v151
	v_exp_f32_e32 v152, v152
	v_exp_f32_e32 v153, v153
	v_exp_f32_e32 v154, v154
	v_exp_f32_e32 v155, v155
	v_pk_add_f32 v[148:149], v[148:149], v[146:147] op_sel:[0,1] op_sel_hi:[1,1]
	v_pk_add_f32 v[150:151], v[150:151], v[146:147] op_sel:[0,1] op_sel_hi:[1,1]
	v_pk_add_f32 v[152:153], v[152:153], v[146:147] op_sel:[0,1] op_sel_hi:[1,1]
	v_pk_add_f32 v[154:155], v[154:155], v[146:147] op_sel:[0,1] op_sel_hi:[1,1]
	v_rcp_f32_e32 v148, v148
	v_rcp_f32_e32 v149, v149
	v_rcp_f32_e32 v150, v150
	v_rcp_f32_e32 v151, v151
	v_rcp_f32_e32 v152, v152
	v_rcp_f32_e32 v153, v153
	v_rcp_f32_e32 v154, v154
	v_rcp_f32_e32 v155, v155
	v_pk_mul_f32 v[26:27], v[26:27], v[148:149]
	v_pk_mul_f32 v[28:29], v[28:29], v[150:151]
	v_pk_mul_f32 v[18:19], v[18:19], v[152:153]
	v_pk_mul_f32 v[20:21], v[20:21], v[154:155]
	v_pk_mul_f32 v[26:27], v[30:31], v[26:27]
	v_pk_mul_f32 v[28:29], v[32:33], v[28:29]
	v_pk_mul_f32 v[18:19], v[22:23], v[18:19]
	v_pk_mul_f32 v[20:21], v[24:25], v[20:21]
	v_cvt_pk_bf16_f32 v156, v26, v27
	v_cvt_pk_bf16_f32 v157, v28, v29
	v_cvt_pk_bf16_f32 v158, v18, v19
	v_cvt_pk_bf16_f32 v159, v20, v21
	v_pk_mul_f32 v[6:7], v[6:7], v[144:145] op_sel:[0,1] op_sel_hi:[1,1]
	v_pk_mul_f32 v[8:9], v[8:9], v[144:145] op_sel:[0,1] op_sel_hi:[1,1]
	v_pk_mul_f32 v[2:3], v[2:3], v[144:145] op_sel:[0,1] op_sel_hi:[1,1]
	v_pk_mul_f32 v[4:5], v[4:5], v[144:145] op_sel:[0,1] op_sel_hi:[1,1]
	v_pk_mul_f32 v[14:15], v[14:15], v[144:145] op_sel:[0,1] op_sel_hi:[1,1]
	v_pk_mul_f32 v[16:17], v[16:17], v[144:145] op_sel:[0,1] op_sel_hi:[1,1]
	v_pk_mul_f32 v[10:11], v[10:11], v[144:145] op_sel:[0,1] op_sel_hi:[1,1]
	v_pk_mul_f32 v[12:13], v[12:13], v[144:145] op_sel:[0,1] op_sel_hi:[1,1]
	v_permlane16_swap_b32_e32 v156, v158
	v_permlane16_swap_b32_e32 v157, v159
	global_store_dwordx4 v[134:135], v[156:159], off
	v_lshl_add_u64 v[134:135], v[134:135], 0, s[12:13]
	v_pk_mul_f32 v[148:149], v[6:7], v[146:147] op_sel_hi:[1,0]
	v_pk_mul_f32 v[150:151], v[8:9], v[146:147] op_sel_hi:[1,0]
	v_pk_mul_f32 v[152:153], v[2:3], v[146:147] op_sel_hi:[1,0]
	v_pk_mul_f32 v[154:155], v[4:5], v[146:147] op_sel_hi:[1,0]
	v_exp_f32_e32 v148, v148
	v_exp_f32_e32 v149, v149
	v_exp_f32_e32 v150, v150
	v_exp_f32_e32 v151, v151
	v_exp_f32_e32 v152, v152
	v_exp_f32_e32 v153, v153
	v_exp_f32_e32 v154, v154
	v_exp_f32_e32 v155, v155
	v_pk_add_f32 v[148:149], v[148:149], v[146:147] op_sel:[0,1] op_sel_hi:[1,1]
	v_pk_add_f32 v[150:151], v[150:151], v[146:147] op_sel:[0,1] op_sel_hi:[1,1]
	v_pk_add_f32 v[152:153], v[152:153], v[146:147] op_sel:[0,1] op_sel_hi:[1,1]
	v_pk_add_f32 v[154:155], v[154:155], v[146:147] op_sel:[0,1] op_sel_hi:[1,1]
	v_rcp_f32_e32 v148, v148
	v_rcp_f32_e32 v149, v149
	v_rcp_f32_e32 v150, v150
	v_rcp_f32_e32 v151, v151
	v_rcp_f32_e32 v152, v152
	v_rcp_f32_e32 v153, v153
	v_rcp_f32_e32 v154, v154
	v_rcp_f32_e32 v155, v155
	v_pk_mul_f32 v[6:7], v[6:7], v[148:149]
	v_pk_mul_f32 v[8:9], v[8:9], v[150:151]
	v_pk_mul_f32 v[2:3], v[2:3], v[152:153]
	v_pk_mul_f32 v[4:5], v[4:5], v[154:155]
	v_pk_mul_f32 v[6:7], v[14:15], v[6:7]
	v_pk_mul_f32 v[8:9], v[16:17], v[8:9]
	v_pk_mul_f32 v[2:3], v[10:11], v[2:3]
	v_pk_mul_f32 v[4:5], v[12:13], v[4:5]
	v_cvt_pk_bf16_f32 v160, v6, v7
	v_cvt_pk_bf16_f32 v161, v8, v9
	v_cvt_pk_bf16_f32 v162, v2, v3
	v_cvt_pk_bf16_f32 v163, v4, v5
	s_nop 1
	v_permlane16_swap_b32_e32 v160, v162
	v_permlane16_swap_b32_e32 v161, v163
	global_store_dwordx4 v[134:135], v[160:163], off
	s_mov_b64 s[12:13], -1
	s_and_b64 vcc, exec, s[0:1]
	s_cbranch_vccnz .LBB0_173

; #define STAGE_B(P, br, kt) do { const char* _gb = (const char*)(Bt + ((long)(br) * K + (long)(kt) * BK)); \
;     __builtin_amdgcn_global_load_lds((const unsigned*)(_gb + bofl0), (unsigned*)((char*)(P) + gtid_ * 16), 16, 0, 0); \
;     __builtin_amdgcn_global_load_lds((const unsigned*)(_gb + (long)K * 128 + bofl0), (unsigned*)((char*)(P) + gtid_ * 16 + 8192), 16, 0, 0); } while (0)
; #define LDA(dst, b, h) for (int m = 0; m < 4; ++m) for (int k = 0; k < 2; ++k) \
;     dst[m][k] = *reinterpret_cast<const bf16x8*>((char*)SA(b, h) + lds_byte(wr * 64 + m * 16 + fr, k * 32 + fq * 8))
; #define LDB(dst, b, h) for (int n = 0; n < 2; ++n) for (int k = 0; k < 2; ++k) \
;     dst[n][k] = *reinterpret_cast<const bf16x8*>((char*)SB(b, h) + lds_byte(wc * 32 + n * 16 + fr, k * 32 + fq * 8))
; #define MMA(ai, bj, At_, Bt_) do { __builtin_amdgcn_s_setprio(1); \
;     for (int m = 0; m < 4; ++m) for (int n = 0; n < 2; ++n) for (int k = 0; k < 2; ++k) \
;       acc[ai][bj][m][n] = __builtin_amdgcn_mfma_f32_16x16x32_bf16(At_[m][k], Bt_[n][k], acc[ai][bj][m][n], 0, 0, 0); \
;     __builtin_amdgcn_s_setprio(0); } while (0)
; #define WAIT_V(n) asm volatile("s_waitcnt vmcnt(" #n ")" ::: "memory")
; #define WAIT_L(n) asm volatile("s_waitcnt lgkmcnt(" #n ")" ::: "memory")
; template <int EPI>
; __device__ __forceinline__ void gemm_tile(const GemmArgs& g, int brow, int bcol, int parity, bool first, bool nvalid, int nbrow, int nbcol) {
;     ...
;   for (int t = 0; t < nt - 2; t += 2) {
;     LDB(B0, 0, 0); SCHED; LDA(At, 0, 0); STAGE_A(SA(1, 1), brow + HALF, t + 1);
;     WAIT_L(8); BAR; WAIT_L(0); MMA(0, 0, At, B0); BAR; SCHED;
;     LDB(B1, 0, 1); STAGE_B(SB(0, 0), bcol, t + 2);
;     BAR; WAIT_L(0); MMA(0, 1, At, B1); BAR; SCHED;
;     LDA(At, 0, 1); STAGE_A(SA(0, 0), brow, t + 2);
;     BAR; WAIT_L(0); MMA(1, 0, At, B0); BAR; SCHED;
;     STAGE_B(SB(0, 1), bcol + HALF, t + 2);
;     WAIT_V(6); BAR; MMA(1, 1, At, B1); BAR; SCHED;
;     LDB(B0, 1, 0); SCHED; LDA(At, 1, 0); STAGE_A(SA(0, 1), brow + HALF, t + 2);
;     WAIT_L(8); BAR; WAIT_L(0); MMA(0, 0, At, B0); BAR; SCHED;
;     LDB(B1, 1, 1); STAGE_B(SB(1, 0), bcol, t + 3);
;     BAR; WAIT_L(0); MMA(0, 1, At, B1); BAR; SCHED;
;     LDA(At, 1, 1); STAGE_A(SA(1, 0), brow, t + 3);
;     BAR; WAIT_L(0); MMA(1, 0, At, B0); BAR; SCHED;
;     STAGE_B(SB(1, 1), bcol + HALF, t + 3);
;     WAIT_V(6); BAR; MMA(1, 1, At, B1); BAR; SCHED;
;   }
.LBB0_166:
	ds_read_b128 v[164:167], v157
	ds_read_b128 v[168:171], v157 offset:1024
	ds_read_b128 v[172:175], v157 offset:2048
	ds_read_b128 v[176:179], v157 offset:3072
	v_add_u32_e32 v161, 0xc000, v137
	v_lshl_add_u64 v[210:211], s[0:1], 0, v[130:131]
	v_readfirstlane_b32 s2, v161
	v_add_u32_e32 v162, 0xe000, v137
	v_lshl_add_u64 v[158:159], v[210:211], 0, s[26:27]
	s_mov_b32 m0, s2
	v_readfirstlane_b32 s2, v162
	ds_read_b128 v[180:183], v147
	ds_read_b128 v[184:187], v147 offset:1024
	ds_read_b128 v[188:191], v146
	ds_read_b128 v[192:195], v146 offset:1024
	ds_read_b128 v[196:199], v145
	ds_read_b128 v[202:205], v145 offset:1024
	ds_read_b128 v[206:209], v144
	ds_read_b128 v[216:219], v144 offset:1024
	global_load_lds_dwordx4 v[158:159], off
	v_lshl_add_u64 v[158:159], v[210:211], 0, s[42:43]
	s_mov_b32 m0, s2
	s_nop 0
	global_load_lds_dwordx4 v[158:159], off
	s_waitcnt lgkmcnt(8)
	s_barrier
	s_waitcnt lgkmcnt(0)
	s_setprio 1
	s_waitcnt lgkmcnt(0)
	v_mfma_f32_16x16x32_bf16 v[126:129], v[164:167], v[180:183], v[126:129]
	v_mfma_f32_16x16x32_bf16 v[122:125], v[172:175], v[180:183], v[122:125]
	v_mfma_f32_16x16x32_bf16 v[118:121], v[164:167], v[188:191], v[118:121]
	v_mfma_f32_16x16x32_bf16 v[114:117], v[172:175], v[188:191], v[114:117]
	v_mfma_f32_16x16x32_bf16 v[110:113], v[164:167], v[196:199], v[110:113]
	v_mfma_f32_16x16x32_bf16 v[106:109], v[172:175], v[196:199], v[106:109]
	v_mfma_f32_16x16x32_bf16 v[102:105], v[164:167], v[206:209], v[102:105]
	v_mfma_f32_16x16x32_bf16 v[98:101], v[172:175], v[206:209], v[98:101]
	v_mfma_f32_16x16x32_bf16 v[126:129], v[168:171], v[184:187], v[126:129]
	v_mfma_f32_16x16x32_bf16 v[122:125], v[176:179], v[184:187], v[122:125]
	v_mfma_f32_16x16x32_bf16 v[118:121], v[168:171], v[192:195], v[118:121]
	v_mfma_f32_16x16x32_bf16 v[114:117], v[176:179], v[192:195], v[114:117]
	v_mfma_f32_16x16x32_bf16 v[110:113], v[168:171], v[202:205], v[110:113]
	v_mfma_f32_16x16x32_bf16 v[106:109], v[176:179], v[202:205], v[106:109]
	v_mfma_f32_16x16x32_bf16 v[102:105], v[168:171], v[216:219], v[102:105]
	v_mfma_f32_16x16x32_bf16 v[98:101], v[176:179], v[216:219], v[98:101]
	s_setprio 0
	s_barrier
	v_add_u32_e32 v158, s15, v142
	v_lshl_add_u64 v[212:213], s[12:13], 0, v[130:131]
	v_readfirstlane_b32 s2, v158
	v_add_u32_e32 v159, 0x2000, v158
	v_lshl_add_u64 v[240:241], v[212:213], 0, s[78:79]
	s_mov_b32 m0, s2
	v_readfirstlane_b32 s2, v159
	ds_read_b128 v[222:225], v154
	ds_read_b128 v[228:231], v154 offset:1024
	ds_read_b128 v[232:235], v154 offset:2048
	ds_read_b128 v[236:239], v154 offset:3072
	global_load_lds_dwordx4 v[240:241], off
	v_lshl_add_u64 v[240:241], v[212:213], 0, s[66:67]
	s_mov_b32 m0, s2
	s_nop 0
	global_load_lds_dwordx4 v[240:241], off
	s_barrier
	s_waitcnt lgkmcnt(0)
	s_setprio 1
	s_waitcnt lgkmcnt(0)
	v_mfma_f32_16x16x32_bf16 v[94:97], v[222:225], v[180:183], v[94:97]
	v_mfma_f32_16x16x32_bf16 v[90:93], v[232:235], v[180:183], v[90:93]
	v_mfma_f32_16x16x32_bf16 v[86:89], v[222:225], v[188:191], v[86:89]
	v_mfma_f32_16x16x32_bf16 v[82:85], v[232:235], v[188:191], v[82:85]
	v_mfma_f32_16x16x32_bf16 v[78:81], v[222:225], v[196:199], v[78:81]
	v_mfma_f32_16x16x32_bf16 v[74:77], v[232:235], v[196:199], v[74:77]
	v_mfma_f32_16x16x32_bf16 v[70:73], v[222:225], v[206:209], v[70:73]
	v_mfma_f32_16x16x32_bf16 v[66:69], v[232:235], v[206:209], v[66:69]
	v_mfma_f32_16x16x32_bf16 v[94:97], v[228:231], v[184:187], v[94:97]
	v_mfma_f32_16x16x32_bf16 v[90:93], v[236:239], v[184:187], v[90:93]
	v_mfma_f32_16x16x32_bf16 v[86:89], v[228:231], v[192:195], v[86:89]
	v_mfma_f32_16x16x32_bf16 v[82:85], v[236:239], v[192:195], v[82:85]
	v_mfma_f32_16x16x32_bf16 v[78:81], v[228:231], v[202:205], v[78:81]
	v_mfma_f32_16x16x32_bf16 v[74:77], v[236:239], v[202:205], v[74:77]
	v_mfma_f32_16x16x32_bf16 v[70:73], v[228:231], v[216:219], v[70:73]
	v_mfma_f32_16x16x32_bf16 v[66:69], v[236:239], v[216:219], v[66:69]
	s_setprio 0
	s_barrier
	v_readfirstlane_b32 s2, v137
	v_lshl_add_u64 v[240:241], v[210:211], 0, s[44:45]
	s_mov_b32 m0, s2
	v_readfirstlane_b32 s2, v136
	ds_read_b128 v[180:183], v147 offset:16384
	ds_read_b128 v[184:187], v147 offset:17408
	ds_read_b128 v[188:191], v146 offset:16384
	ds_read_b128 v[192:195], v146 offset:17408
	ds_read_b128 v[196:199], v145 offset:16384
	ds_read_b128 v[202:205], v145 offset:17408
	ds_read_b128 v[206:209], v144 offset:16384
	ds_read_b128 v[216:219], v144 offset:17408
	global_load_lds_dwordx4 v[240:241], off
	v_lshl_add_u64 v[240:241], v[210:211], 0, s[46:47]
	s_mov_b32 m0, s2
	s_nop 0
	global_load_lds_dwordx4 v[240:241], off
	s_barrier
	s_waitcnt lgkmcnt(0)
	s_setprio 1
	s_waitcnt lgkmcnt(0)
	v_mfma_f32_16x16x32_bf16 v[62:65], v[164:167], v[180:183], v[62:65]
	v_mfma_f32_16x16x32_bf16 v[58:61], v[172:175], v[180:183], v[58:61]
	v_mfma_f32_16x16x32_bf16 v[54:57], v[164:167], v[188:191], v[54:57]
	v_mfma_f32_16x16x32_bf16 v[50:53], v[172:175], v[188:191], v[50:53]
	v_mfma_f32_16x16x32_bf16 v[46:49], v[164:167], v[196:199], v[46:49]
	v_mfma_f32_16x16x32_bf16 v[42:45], v[172:175], v[196:199], v[42:45]
	v_mfma_f32_16x16x32_bf16 v[38:41], v[164:167], v[206:209], v[38:41]
	v_mfma_f32_16x16x32_bf16 v[34:37], v[172:175], v[206:209], v[34:37]
	v_mfma_f32_16x16x32_bf16 v[62:65], v[168:171], v[184:187], v[62:65]
	v_mfma_f32_16x16x32_bf16 v[58:61], v[176:179], v[184:187], v[58:61]
	v_mfma_f32_16x16x32_bf16 v[54:57], v[168:171], v[192:195], v[54:57]
	v_mfma_f32_16x16x32_bf16 v[50:53], v[176:179], v[192:195], v[50:53]
	v_mfma_f32_16x16x32_bf16 v[46:49], v[168:171], v[202:205], v[46:49]
	v_mfma_f32_16x16x32_bf16 v[42:45], v[176:179], v[202:205], v[42:45]
	v_mfma_f32_16x16x32_bf16 v[38:41], v[168:171], v[216:219], v[38:41]
	v_mfma_f32_16x16x32_bf16 v[34:37], v[176:179], v[216:219], v[34:37]
	s_setprio 0
	s_barrier
; #define STAGE_B(P, br, kt) do { const char* _gb = (const char*)(Bt + ((long)(br) * K + (long)(kt) * BK)); \
;     __builtin_amdgcn_global_load_lds((const unsigned*)(_gb + bofl0), (unsigned*)((char*)(P) + gtid_ * 16), 16, 0, 0); \
;     __builtin_amdgcn_global_load_lds((const unsigned*)(_gb + (long)K * 128 + bofl0), (unsigned*)((char*)(P) + gtid_ * 16 + 8192), 16, 0, 0); } while (0)
; #define LDA(dst, b, h) for (int m = 0; m < 4; ++m) for (int k = 0; k < 2; ++k) \
;     dst[m][k] = *reinterpret_cast<const bf16x8*>((char*)SA(b, h) + lds_byte(wr * 64 + m * 16 + fr, k * 32 + fq * 8))
; #define LDB(dst, b, h) for (int n = 0; n < 2; ++n) for (int k = 0; k < 2; ++k) \
;     dst[n][k] = *reinterpret_cast<const bf16x8*>((char*)SB(b, h) + lds_byte(wc * 32 + n * 16 + fr, k * 32 + fq * 8))
; #define MMA(ai, bj, At_, Bt_) do { __builtin_amdgcn_s_setprio(1); \
;     for (int m = 0; m < 4; ++m) for (int n = 0; n < 2; ++n) for (int k = 0; k < 2; ++k) \
;       acc[ai][bj][m][n] = __builtin_amdgcn_mfma_f32_16x16x32_bf16(At_[m][k], Bt_[n][k], acc[ai][bj][m][n], 0, 0, 0); \
;     __builtin_amdgcn_s_setprio(0); } while (0)
; #define WAIT_V(n) asm volatile("s_waitcnt vmcnt(" #n ")" ::: "memory")
; #define WAIT_L(n) asm volatile("s_waitcnt lgkmcnt(" #n ")" ::: "memory")
; template <int EPI>
; __device__ __forceinline__ void gemm_tile(const GemmArgs& g, int brow, int bcol, int parity, bool first, bool nvalid, int nbrow, int nbcol) {
;     ...
;   for (int t = 0; t < nt - 2; t += 2) {
;     LDB(B0, 0, 0); SCHED; LDA(At, 0, 0); STAGE_A(SA(1, 1), brow + HALF, t + 1);
;     WAIT_L(8); BAR; WAIT_L(0); MMA(0, 0, At, B0); BAR; SCHED;
;     LDB(B1, 0, 1); STAGE_B(SB(0, 0), bcol, t + 2);
;     BAR; WAIT_L(0); MMA(0, 1, At, B1); BAR; SCHED;
;     LDA(At, 0, 1); STAGE_A(SA(0, 0), brow, t + 2);
;     BAR; WAIT_L(0); MMA(1, 0, At, B0); BAR; SCHED;
;     STAGE_B(SB(0, 1), bcol + HALF, t + 2);
;     WAIT_V(6); BAR; MMA(1, 1, At, B1); BAR; SCHED;
;     LDB(B0, 1, 0); SCHED; LDA(At, 1, 0); STAGE_A(SA(0, 1), brow + HALF, t + 2);
;     WAIT_L(8); BAR; WAIT_L(0); MMA(0, 0, At, B0); BAR; SCHED;
;     LDB(B1, 1, 1); STAGE_B(SB(1, 0), bcol, t + 3);
;     BAR; WAIT_L(0); MMA(0, 1, At, B1); BAR; SCHED;
;     LDA(At, 1, 1); STAGE_A(SA(1, 0), brow, t + 3);
;     BAR; WAIT_L(0); MMA(1, 0, At, B0); BAR; SCHED;
;     STAGE_B(SB(1, 1), bcol + HALF, t + 3);
;     WAIT_V(6); BAR; MMA(1, 1, At, B1); BAR; SCHED;
;   }
	v_readfirstlane_b32 s2, v135
	v_add_u32_e32 v160, 0x2000, v135
	v_lshl_add_u64 v[164:165], v[212:213], 0, s[76:77]
	s_mov_b32 m0, s2
	v_readfirstlane_b32 s2, v160
	global_load_lds_dwordx4 v[164:165], off
	v_lshl_add_u64 v[164:165], v[212:213], 0, s[96:97]
	s_mov_b32 m0, s2
	s_nop 0
	global_load_lds_dwordx4 v[164:165], off
	s_waitcnt vmcnt(6)
	s_barrier
	s_setprio 1
	v_mfma_f32_16x16x32_bf16 v[30:33], v[222:225], v[180:183], v[30:33]
	v_mfma_f32_16x16x32_bf16 v[26:29], v[232:235], v[180:183], v[26:29]
	v_mfma_f32_16x16x32_bf16 v[22:25], v[222:225], v[188:191], v[22:25]
	v_mfma_f32_16x16x32_bf16 v[18:21], v[232:235], v[188:191], v[18:21]
	v_mfma_f32_16x16x32_bf16 v[14:17], v[222:225], v[196:199], v[14:17]
	v_mfma_f32_16x16x32_bf16 v[10:13], v[232:235], v[196:199], v[10:13]
	v_mfma_f32_16x16x32_bf16 v[6:9], v[222:225], v[206:209], v[6:9]
	v_mfma_f32_16x16x32_bf16 v[2:5], v[232:235], v[206:209], v[2:5]
	v_mfma_f32_16x16x32_bf16 v[30:33], v[228:231], v[184:187], v[30:33]
	v_mfma_f32_16x16x32_bf16 v[26:29], v[236:239], v[184:187], v[26:29]
	v_mfma_f32_16x16x32_bf16 v[22:25], v[228:231], v[192:195], v[22:25]
	v_mfma_f32_16x16x32_bf16 v[18:21], v[236:239], v[192:195], v[18:21]
	v_mfma_f32_16x16x32_bf16 v[14:17], v[228:231], v[202:205], v[14:17]
	v_mfma_f32_16x16x32_bf16 v[10:13], v[236:239], v[202:205], v[10:13]
	v_mfma_f32_16x16x32_bf16 v[6:9], v[228:231], v[216:219], v[6:9]
	v_mfma_f32_16x16x32_bf16 v[2:5], v[236:239], v[216:219], v[2:5]
	s_setprio 0
	s_barrier
	ds_read_b128 v[164:167], v149
	ds_read_b128 v[168:171], v149 offset:1024
	ds_read_b128 v[172:175], v149 offset:2048
	ds_read_b128 v[176:179], v149 offset:3072
	v_readfirstlane_b32 s2, v134
	v_lshl_add_u64 v[222:223], v[210:211], 0, s[48:49]
	s_mov_b32 m0, s2
	v_readfirstlane_b32 s2, v133
	ds_read_b128 v[180:183], v147 offset:32768
	ds_read_b128 v[184:187], v147 offset:33792
	ds_read_b128 v[188:191], v146 offset:32768
	ds_read_b128 v[192:195], v146 offset:33792
	ds_read_b128 v[196:199], v145 offset:32768
	ds_read_b128 v[202:205], v145 offset:33792
	ds_read_b128 v[206:209], v144 offset:32768
	ds_read_b128 v[216:219], v144 offset:33792
	global_load_lds_dwordx4 v[222:223], off
	v_lshl_add_u64 v[222:223], v[210:211], 0, s[50:51]
	s_mov_b32 m0, s2
	s_nop 0
	global_load_lds_dwordx4 v[222:223], off
	s_waitcnt lgkmcnt(8)
	s_barrier
	s_waitcnt lgkmcnt(0)
	s_setprio 1
	s_waitcnt lgkmcnt(0)
	v_mfma_f32_16x16x32_bf16 v[126:129], v[164:167], v[180:183], v[126:129]
	v_mfma_f32_16x16x32_bf16 v[122:125], v[172:175], v[180:183], v[122:125]
	v_mfma_f32_16x16x32_bf16 v[118:121], v[164:167], v[188:191], v[118:121]
	v_mfma_f32_16x16x32_bf16 v[114:117], v[172:175], v[188:191], v[114:117]
	v_mfma_f32_16x16x32_bf16 v[110:113], v[164:167], v[196:199], v[110:113]
	v_mfma_f32_16x16x32_bf16 v[106:109], v[172:175], v[196:199], v[106:109]
	v_mfma_f32_16x16x32_bf16 v[102:105], v[164:167], v[206:209], v[102:105]
	v_mfma_f32_16x16x32_bf16 v[98:101], v[172:175], v[206:209], v[98:101]
	v_mfma_f32_16x16x32_bf16 v[126:129], v[168:171], v[184:187], v[126:129]
	v_mfma_f32_16x16x32_bf16 v[122:125], v[176:179], v[184:187], v[122:125]
	v_mfma_f32_16x16x32_bf16 v[118:121], v[168:171], v[192:195], v[118:121]
	v_mfma_f32_16x16x32_bf16 v[114:117], v[176:179], v[192:195], v[114:117]
	v_mfma_f32_16x16x32_bf16 v[110:113], v[168:171], v[202:205], v[110:113]
	v_mfma_f32_16x16x32_bf16 v[106:109], v[176:179], v[202:205], v[106:109]
	v_mfma_f32_16x16x32_bf16 v[102:105], v[168:171], v[216:219], v[102:105]
	v_mfma_f32_16x16x32_bf16 v[98:101], v[176:179], v[216:219], v[98:101]
	s_setprio 0
	s_barrier
	v_readfirstlane_b32 s2, v150
	v_lshl_add_u64 v[240:241], v[212:213], 0, s[58:59]
	s_mov_b32 m0, s2
	v_readfirstlane_b32 s2, v151
	ds_read_b128 v[222:225], v148
	ds_read_b128 v[228:231], v148 offset:1024
	ds_read_b128 v[232:235], v148 offset:2048
	ds_read_b128 v[236:239], v148 offset:3072
	global_load_lds_dwordx4 v[240:241], off
	v_lshl_add_u64 v[240:241], v[212:213], 0, vcc
	s_mov_b32 m0, s2
	s_nop 0
	global_load_lds_dwordx4 v[240:241], off
	s_barrier
	s_waitcnt lgkmcnt(0)
	s_setprio 1
	s_waitcnt lgkmcnt(0)
	v_mfma_f32_16x16x32_bf16 v[94:97], v[222:225], v[180:183], v[94:97]
	v_mfma_f32_16x16x32_bf16 v[90:93], v[232:235], v[180:183], v[90:93]
	v_mfma_f32_16x16x32_bf16 v[86:89], v[222:225], v[188:191], v[86:89]
	v_mfma_f32_16x16x32_bf16 v[82:85], v[232:235], v[188:191], v[82:85]
	v_mfma_f32_16x16x32_bf16 v[78:81], v[222:225], v[196:199], v[78:81]
	v_mfma_f32_16x16x32_bf16 v[74:77], v[232:235], v[196:199], v[74:77]
	v_mfma_f32_16x16x32_bf16 v[70:73], v[222:225], v[206:209], v[70:73]
	v_mfma_f32_16x16x32_bf16 v[66:69], v[232:235], v[206:209], v[66:69]
	v_mfma_f32_16x16x32_bf16 v[94:97], v[228:231], v[184:187], v[94:97]
	v_mfma_f32_16x16x32_bf16 v[90:93], v[236:239], v[184:187], v[90:93]
	v_mfma_f32_16x16x32_bf16 v[86:89], v[228:231], v[192:195], v[86:89]
	v_mfma_f32_16x16x32_bf16 v[82:85], v[236:239], v[192:195], v[82:85]
	v_mfma_f32_16x16x32_bf16 v[78:81], v[228:231], v[202:205], v[78:81]
	v_mfma_f32_16x16x32_bf16 v[74:77], v[236:239], v[202:205], v[74:77]
	v_mfma_f32_16x16x32_bf16 v[70:73], v[228:231], v[216:219], v[70:73]
	v_mfma_f32_16x16x32_bf16 v[66:69], v[236:239], v[216:219], v[66:69]
	s_setprio 0
	s_barrier
	v_readfirstlane_b32 s2, v152
	v_lshl_add_u64 v[240:241], v[210:211], 0, s[52:53]
	s_mov_b32 m0, s2
	v_readfirstlane_b32 s2, v153
	ds_read_b128 v[180:183], v147 offset:49152
	ds_read_b128 v[184:187], v147 offset:50176
	ds_read_b128 v[188:191], v146 offset:49152
	ds_read_b128 v[192:195], v146 offset:50176
	ds_read_b128 v[196:199], v145 offset:49152
	ds_read_b128 v[202:205], v145 offset:50176
	ds_read_b128 v[206:209], v144 offset:49152
	ds_read_b128 v[216:219], v144 offset:50176
	global_load_lds_dwordx4 v[240:241], off
	v_lshl_add_u64 v[210:211], v[210:211], 0, s[56:57]
	s_mov_b32 m0, s2
	s_nop 0
	global_load_lds_dwordx4 v[210:211], off
	s_barrier
; #define STAGE_B(P, br, kt) do { const char* _gb = (const char*)(Bt + ((long)(br) * K + (long)(kt) * BK)); \
;     __builtin_amdgcn_global_load_lds((const unsigned*)(_gb + bofl0), (unsigned*)((char*)(P) + gtid_ * 16), 16, 0, 0); \
;     __builtin_amdgcn_global_load_lds((const unsigned*)(_gb + (long)K * 128 + bofl0), (unsigned*)((char*)(P) + gtid_ * 16 + 8192), 16, 0, 0); } while (0)
; #define LDA(dst, b, h) for (int m = 0; m < 4; ++m) for (int k = 0; k < 2; ++k) \
;     dst[m][k] = *reinterpret_cast<const bf16x8*>((char*)SA(b, h) + lds_byte(wr * 64 + m * 16 + fr, k * 32 + fq * 8))
; #define LDB(dst, b, h) for (int n = 0; n < 2; ++n) for (int k = 0; k < 2; ++k) \
;     dst[n][k] = *reinterpret_cast<const bf16x8*>((char*)SB(b, h) + lds_byte(wc * 32 + n * 16 + fr, k * 32 + fq * 8))
; #define MMA(ai, bj, At_, Bt_) do { __builtin_amdgcn_s_setprio(1); \
;     for (int m = 0; m < 4; ++m) for (int n = 0; n < 2; ++n) for (int k = 0; k < 2; ++k) \
;       acc[ai][bj][m][n] = __builtin_amdgcn_mfma_f32_16x16x32_bf16(At_[m][k], Bt_[n][k], acc[ai][bj][m][n], 0, 0, 0); \
;     __builtin_amdgcn_s_setprio(0); } while (0)
; #define WAIT_V(n) asm volatile("s_waitcnt vmcnt(" #n ")" ::: "memory")
; #define WAIT_L(n) asm volatile("s_waitcnt lgkmcnt(" #n ")" ::: "memory")
; #define BAR __builtin_amdgcn_s_barrier()
; #define SCHED __builtin_amdgcn_sched_barrier(0)
; template <int EPI>
; __device__ __forceinline__ void gemm_tile(const GemmArgs& g, int brow, int bcol, int parity, bool first, bool nvalid, int nbrow, int nbcol) {
;     ...
;     BAR; WAIT_L(0); MMA(0, 1, At, B1); BAR; SCHED;
;     LDA(At, 1, 1); STAGE_A(SA(1, 0), brow, t + 3);
;     BAR; WAIT_L(0); MMA(1, 0, At, B0); BAR; SCHED;
;     STAGE_B(SB(1, 1), bcol + HALF, t + 3);
;     WAIT_V(6); BAR; MMA(1, 1, At, B1); BAR; SCHED;
;   }
;   { LDB(B0, 0, 0); LDA(At, 0, 0); STAGE_A(SA(1, 1), brow + HALF, nt - 1);
;     BAR; WAIT_L(0); MMA(0, 0, At, B0); BAR;
	s_waitcnt lgkmcnt(0)
	s_setprio 1
	s_waitcnt lgkmcnt(0)
	v_mfma_f32_16x16x32_bf16 v[62:65], v[164:167], v[180:183], v[62:65]
	v_mfma_f32_16x16x32_bf16 v[58:61], v[172:175], v[180:183], v[58:61]
	v_mfma_f32_16x16x32_bf16 v[54:57], v[164:167], v[188:191], v[54:57]
	v_mfma_f32_16x16x32_bf16 v[50:53], v[172:175], v[188:191], v[50:53]
	v_mfma_f32_16x16x32_bf16 v[46:49], v[164:167], v[196:199], v[46:49]
	v_mfma_f32_16x16x32_bf16 v[42:45], v[172:175], v[196:199], v[42:45]
	v_mfma_f32_16x16x32_bf16 v[38:41], v[164:167], v[206:209], v[38:41]
	v_mfma_f32_16x16x32_bf16 v[34:37], v[172:175], v[206:209], v[34:37]
	v_mfma_f32_16x16x32_bf16 v[62:65], v[168:171], v[184:187], v[62:65]
	v_mfma_f32_16x16x32_bf16 v[58:61], v[176:179], v[184:187], v[58:61]
	v_mfma_f32_16x16x32_bf16 v[54:57], v[168:171], v[192:195], v[54:57]
	v_mfma_f32_16x16x32_bf16 v[50:53], v[176:179], v[192:195], v[50:53]
	v_mfma_f32_16x16x32_bf16 v[46:49], v[168:171], v[202:205], v[46:49]
	v_mfma_f32_16x16x32_bf16 v[42:45], v[176:179], v[202:205], v[42:45]
	v_mfma_f32_16x16x32_bf16 v[38:41], v[168:171], v[216:219], v[38:41]
	v_mfma_f32_16x16x32_bf16 v[34:37], v[176:179], v[216:219], v[34:37]
	s_setprio 0
	s_barrier
	v_readfirstlane_b32 s2, v155
	v_lshl_add_u64 v[164:165], v[212:213], 0, s[60:61]
	s_mov_b32 m0, s2
	v_readfirstlane_b32 s2, v156
	global_load_lds_dwordx4 v[164:165], off
	v_lshl_add_u64 v[164:165], v[212:213], 0, s[94:95]
	s_mov_b32 m0, s2
	s_nop 0
	global_load_lds_dwordx4 v[164:165], off
	s_waitcnt vmcnt(6)
	s_barrier
	s_setprio 1
	v_mfma_f32_16x16x32_bf16 v[30:33], v[222:225], v[180:183], v[30:33]
	v_mfma_f32_16x16x32_bf16 v[26:29], v[232:235], v[180:183], v[26:29]
	v_mfma_f32_16x16x32_bf16 v[22:25], v[222:225], v[188:191], v[22:25]
	v_mfma_f32_16x16x32_bf16 v[18:21], v[232:235], v[188:191], v[18:21]
	v_mfma_f32_16x16x32_bf16 v[14:17], v[222:225], v[196:199], v[14:17]
	v_mfma_f32_16x16x32_bf16 v[10:13], v[232:235], v[196:199], v[10:13]
	v_mfma_f32_16x16x32_bf16 v[6:9], v[222:225], v[206:209], v[6:9]
	v_mfma_f32_16x16x32_bf16 v[2:5], v[232:235], v[206:209], v[2:5]
	v_mfma_f32_16x16x32_bf16 v[30:33], v[228:231], v[184:187], v[30:33]
	v_mfma_f32_16x16x32_bf16 v[26:29], v[236:239], v[184:187], v[26:29]
	v_mfma_f32_16x16x32_bf16 v[22:25], v[228:231], v[192:195], v[22:25]
	v_mfma_f32_16x16x32_bf16 v[18:21], v[236:239], v[192:195], v[18:21]
	v_mfma_f32_16x16x32_bf16 v[14:17], v[228:231], v[202:205], v[14:17]
	v_mfma_f32_16x16x32_bf16 v[10:13], v[236:239], v[202:205], v[10:13]
	v_mfma_f32_16x16x32_bf16 v[6:9], v[228:231], v[216:219], v[6:9]
	v_mfma_f32_16x16x32_bf16 v[2:5], v[236:239], v[216:219], v[2:5]
	s_setprio 0
	s_barrier
	s_add_i32 s25, s25, 2
	s_add_u32 s0, s0, 0x100
	s_addc_u32 s1, s1, 0
	s_add_u32 s12, s12, 0x100
	s_addc_u32 s13, s13, 0
	s_cmp_lt_u32 s25, 12
	s_cbranch_scc1 .LBB0_166
	s_or_b32 s0, s38, 0x80
	s_ashr_i32 s1, s0, 31
	s_lshl_b64 s[0:1], s[0:1], 11
	s_add_u32 s0, s80, s0
	s_addc_u32 s1, s81, s1
	v_lshl_add_u64 v[130:131], s[0:1], 0, v[0:1]
	s_mov_b64 s[0:1], 0x780
	ds_read_b128 v[150:153], v157
	ds_read_b128 v[164:167], v157 offset:1024
	ds_read_b128 v[168:171], v157 offset:2048
	ds_read_b128 v[172:175], v157 offset:3072
	ds_read_b128 v[176:179], v147
	ds_read_b128 v[180:183], v147 offset:1024
	ds_read_b128 v[184:187], v146
	ds_read_b128 v[188:191], v146 offset:1024
	ds_read_b128 v[192:195], v145
	ds_read_b128 v[196:199], v145 offset:1024
	ds_read_b128 v[202:205], v144
	ds_read_b128 v[206:209], v144 offset:1024
	v_lshl_add_u64 v[156:157], v[130:131], 0, s[0:1]
	v_readfirstlane_b32 s0, v161
	s_mov_b32 m0, s0
	s_mov_b64 s[0:1], 0x20780
	v_lshl_add_u64 v[130:131], v[130:131], 0, s[0:1]
	v_readfirstlane_b32 s0, v162
	global_load_lds_dwordx4 v[156:157], off
	s_mov_b32 m0, s0
	s_nop 0
	global_load_lds_dwordx4 v[130:131], off
	s_barrier
	s_waitcnt lgkmcnt(0)
	s_setprio 1
	s_waitcnt lgkmcnt(0)
	v_mfma_f32_16x16x32_bf16 v[126:129], v[150:153], v[176:179], v[126:129]
	v_mfma_f32_16x16x32_bf16 v[118:121], v[150:153], v[184:187], v[118:121]
	v_mfma_f32_16x16x32_bf16 v[110:113], v[150:153], v[192:195], v[110:113]
	v_mfma_f32_16x16x32_bf16 v[102:105], v[150:153], v[202:205], v[102:105]
	v_mfma_f32_16x16x32_bf16 v[126:129], v[164:167], v[180:183], v[126:129]
	v_mfma_f32_16x16x32_bf16 v[122:125], v[168:171], v[176:179], v[122:125]
	v_mfma_f32_16x16x32_bf16 v[118:121], v[164:167], v[188:191], v[118:121]
	v_mfma_f32_16x16x32_bf16 v[114:117], v[168:171], v[184:187], v[114:117]
	v_mfma_f32_16x16x32_bf16 v[110:113], v[164:167], v[196:199], v[110:113]
	v_mfma_f32_16x16x32_bf16 v[106:109], v[168:171], v[192:195], v[106:109]
	v_mfma_f32_16x16x32_bf16 v[102:105], v[164:167], v[206:209], v[102:105]
	v_mfma_f32_16x16x32_bf16 v[98:101], v[168:171], v[202:205], v[98:101]
	v_mfma_f32_16x16x32_bf16 v[216:219], v[172:175], v[180:183], v[122:125]
	v_mfma_f32_16x16x32_bf16 v[222:225], v[172:175], v[188:191], v[114:117]
	v_mfma_f32_16x16x32_bf16 v[228:231], v[172:175], v[196:199], v[106:109]
	v_mfma_f32_16x16x32_bf16 v[232:235], v[172:175], v[206:209], v[98:101]
	s_setprio 0
	s_barrier
	s_nop 1
	ds_read_b128 v[98:101], v154
	ds_read_b128 v[106:109], v154 offset:1024
	ds_read_b128 v[114:117], v154 offset:2048
	ds_read_b128 v[122:125], v154 offset:3072
	s_barrier
; #define LDA(dst, b, h) for (int m = 0; m < 4; ++m) for (int k = 0; k < 2; ++k) \
;     dst[m][k] = *reinterpret_cast<const bf16x8*>((char*)SA(b, h) + lds_byte(wr * 64 + m * 16 + fr, k * 32 + fq * 8))
; #define LDB(dst, b, h) for (int n = 0; n < 2; ++n) for (int k = 0; k < 2; ++k) \
;     dst[n][k] = *reinterpret_cast<const bf16x8*>((char*)SB(b, h) + lds_byte(wc * 32 + n * 16 + fr, k * 32 + fq * 8))
; #define MMA(ai, bj, At_, Bt_) do { __builtin_amdgcn_s_setprio(1); \
;     for (int m = 0; m < 4; ++m) for (int n = 0; n < 2; ++n) for (int k = 0; k < 2; ++k) \
;       acc[ai][bj][m][n] = __builtin_amdgcn_mfma_f32_16x16x32_bf16(At_[m][k], Bt_[n][k], acc[ai][bj][m][n], 0, 0, 0); \
;     __builtin_amdgcn_s_setprio(0); } while (0)
; #define WAIT_V(n) asm volatile("s_waitcnt vmcnt(" #n ")" ::: "memory")
; #define WAIT_L(n) asm volatile("s_waitcnt lgkmcnt(" #n ")" ::: "memory")
; #define BAR __builtin_amdgcn_s_barrier()
; #define SCHED __builtin_amdgcn_sched_barrier(0)
; template <int EPI>
; __device__ __forceinline__ void gemm_tile(const GemmArgs& g, int brow, int bcol, int parity, bool first, bool nvalid, int nbrow, int nbcol) {
;     ...
;   { LDB(B0, 0, 0); LDA(At, 0, 0); STAGE_A(SA(1, 1), brow + HALF, nt - 1);
;     BAR; WAIT_L(0); MMA(0, 0, At, B0); BAR;
;     LDB(B1, 0, 1); BAR; WAIT_L(0); MMA(0, 1, At, B1); BAR; SCHED;
;     LDA(At, 0, 1); WAIT_V(4); BAR; WAIT_L(0); MMA(1, 0, At, B0); MMA(1, 1, At, B1); BAR; }
;   { LDB(B0, 1, 0); LDA(At, 1, 0); WAIT_V(2); BAR; WAIT_L(0); MMA(0, 0, At, B0); BAR;
	s_waitcnt lgkmcnt(0)
	s_setprio 1
	s_waitcnt lgkmcnt(0)
	v_mfma_f32_16x16x32_bf16 v[94:97], v[98:101], v[176:179], v[94:97]
	v_mfma_f32_16x16x32_bf16 v[86:89], v[98:101], v[184:187], v[86:89]
	v_mfma_f32_16x16x32_bf16 v[78:81], v[98:101], v[192:195], v[78:81]
	v_mfma_f32_16x16x32_bf16 v[74:77], v[114:117], v[192:195], v[74:77]
	v_mfma_f32_16x16x32_bf16 v[94:97], v[106:109], v[180:183], v[94:97]
	v_mfma_f32_16x16x32_bf16 v[90:93], v[114:117], v[176:179], v[90:93]
	v_mfma_f32_16x16x32_bf16 v[86:89], v[106:109], v[188:191], v[86:89]
	v_mfma_f32_16x16x32_bf16 v[82:85], v[114:117], v[184:187], v[82:85]
	v_mfma_f32_16x16x32_bf16 v[78:81], v[106:109], v[196:199], v[78:81]
	v_mfma_f32_16x16x32_bf16 v[74:77], v[122:125], v[196:199], v[74:77]
	v_mfma_f32_16x16x32_bf16 v[70:73], v[98:101], v[202:205], v[70:73]
	v_mfma_f32_16x16x32_bf16 v[66:69], v[114:117], v[202:205], v[66:69]
	v_mfma_f32_16x16x32_bf16 v[154:157], v[122:125], v[180:183], v[90:93]
	v_mfma_f32_16x16x32_bf16 v[176:179], v[122:125], v[188:191], v[82:85]
	v_mfma_f32_16x16x32_bf16 v[180:183], v[106:109], v[206:209], v[70:73]
	v_mfma_f32_16x16x32_bf16 v[184:187], v[122:125], v[206:209], v[66:69]
	s_setprio 0
	s_barrier
	s_nop 1
	ds_read_b128 v[66:69], v147 offset:16384
	ds_read_b128 v[70:73], v147 offset:17408
	ds_read_b128 v[82:85], v146 offset:16384
	ds_read_b128 v[90:93], v146 offset:17408
	ds_read_b128 v[188:191], v145 offset:16384
	ds_read_b128 v[192:195], v145 offset:17408
	ds_read_b128 v[196:199], v144 offset:16384
	ds_read_b128 v[202:205], v144 offset:17408
	s_waitcnt vmcnt(4)
	s_barrier
	s_waitcnt lgkmcnt(0)
	s_setprio 1
	s_waitcnt lgkmcnt(0)
	v_mfma_f32_16x16x32_bf16 v[62:65], v[150:153], v[66:69], v[62:65]
	v_mfma_f32_16x16x32_bf16 v[54:57], v[150:153], v[82:85], v[54:57]
	v_mfma_f32_16x16x32_bf16 v[46:49], v[150:153], v[188:191], v[46:49]
	v_mfma_f32_16x16x32_bf16 v[38:41], v[150:153], v[196:199], v[38:41]
	v_mfma_f32_16x16x32_bf16 v[62:65], v[164:167], v[70:73], v[62:65]
	v_mfma_f32_16x16x32_bf16 v[58:61], v[168:171], v[66:69], v[58:61]
	v_mfma_f32_16x16x32_bf16 v[54:57], v[164:167], v[90:93], v[54:57]
	v_mfma_f32_16x16x32_bf16 v[50:53], v[168:171], v[82:85], v[50:53]
	v_mfma_f32_16x16x32_bf16 v[46:49], v[164:167], v[192:195], v[46:49]
	v_mfma_f32_16x16x32_bf16 v[42:45], v[168:171], v[188:191], v[42:45]
	v_mfma_f32_16x16x32_bf16 v[38:41], v[164:167], v[202:205], v[38:41]
	v_mfma_f32_16x16x32_bf16 v[34:37], v[168:171], v[196:199], v[34:37]
	v_mfma_f32_16x16x32_bf16 v[206:209], v[172:175], v[70:73], v[58:61]
	v_mfma_f32_16x16x32_bf16 v[236:239], v[172:175], v[90:93], v[50:53]
	v_mfma_f32_16x16x32_bf16 v[240:243], v[172:175], v[192:195], v[42:45]
	v_mfma_f32_16x16x32_bf16 v[150:153], v[172:175], v[202:205], v[34:37]
	s_setprio 0
	s_setprio 1
	v_mfma_f32_16x16x32_bf16 v[30:33], v[98:101], v[66:69], v[30:33]
	v_mfma_f32_16x16x32_bf16 v[22:25], v[98:101], v[82:85], v[22:25]
	v_mfma_f32_16x16x32_bf16 v[14:17], v[98:101], v[188:191], v[14:17]
	v_mfma_f32_16x16x32_bf16 v[10:13], v[114:117], v[188:191], v[10:13]
	v_mfma_f32_16x16x32_bf16 v[30:33], v[106:109], v[70:73], v[30:33]
	v_mfma_f32_16x16x32_bf16 v[26:29], v[114:117], v[66:69], v[26:29]
	v_mfma_f32_16x16x32_bf16 v[22:25], v[106:109], v[90:93], v[22:25]
	v_mfma_f32_16x16x32_bf16 v[18:21], v[114:117], v[82:85], v[18:21]
	v_mfma_f32_16x16x32_bf16 v[14:17], v[106:109], v[192:195], v[14:17]
	v_mfma_f32_16x16x32_bf16 v[10:13], v[122:125], v[192:195], v[10:13]
	v_mfma_f32_16x16x32_bf16 v[6:9], v[98:101], v[196:199], v[6:9]
	v_mfma_f32_16x16x32_bf16 v[2:5], v[114:117], v[196:199], v[2:5]
	v_mfma_f32_16x16x32_bf16 v[162:165], v[122:125], v[70:73], v[26:29]
	v_mfma_f32_16x16x32_bf16 v[166:169], v[122:125], v[90:93], v[18:21]
	v_mfma_f32_16x16x32_bf16 v[170:173], v[106:109], v[202:205], v[6:9]
	v_mfma_f32_16x16x32_bf16 v[188:191], v[122:125], v[202:205], v[2:5]
	s_setprio 0
	s_barrier
	s_nop 1
	ds_read_b128 v[2:5], v149
	ds_read_b128 v[6:9], v149 offset:1024
	ds_read_b128 v[192:195], v149 offset:2048
	ds_read_b128 v[196:199], v149 offset:3072
	ds_read_b128 v[18:21], v147 offset:32768
	ds_read_b128 v[26:29], v147 offset:33792
	ds_read_b128 v[34:37], v146 offset:32768
	ds_read_b128 v[42:45], v146 offset:33792
	ds_read_b128 v[50:53], v145 offset:32768
	ds_read_b128 v[58:61], v145 offset:33792
	ds_read_b128 v[202:205], v144 offset:32768
	ds_read_b128 v[244:247], v144 offset:33792
	s_waitcnt vmcnt(2)
	s_barrier
; #define LDA(dst, b, h) for (int m = 0; m < 4; ++m) for (int k = 0; k < 2; ++k) \
;     dst[m][k] = *reinterpret_cast<const bf16x8*>((char*)SA(b, h) + lds_byte(wr * 64 + m * 16 + fr, k * 32 + fq * 8))
; #define LDB(dst, b, h) for (int n = 0; n < 2; ++n) for (int k = 0; k < 2; ++k) \
;     dst[n][k] = *reinterpret_cast<const bf16x8*>((char*)SB(b, h) + lds_byte(wc * 32 + n * 16 + fr, k * 32 + fq * 8))
; #define MMA(ai, bj, At_, Bt_) do { __builtin_amdgcn_s_setprio(1); \
;     for (int m = 0; m < 4; ++m) for (int n = 0; n < 2; ++n) for (int k = 0; k < 2; ++k) \
;       acc[ai][bj][m][n] = __builtin_amdgcn_mfma_f32_16x16x32_bf16(At_[m][k], Bt_[n][k], acc[ai][bj][m][n], 0, 0, 0); \
;     __builtin_amdgcn_s_setprio(0); } while (0)
; #define WAIT_V(n) asm volatile("s_waitcnt vmcnt(" #n ")" ::: "memory")
; #define WAIT_L(n) asm volatile("s_waitcnt lgkmcnt(" #n ")" ::: "memory")
; #define BAR __builtin_amdgcn_s_barrier()
; #define SCHED __builtin_amdgcn_sched_barrier(0)
; template <int EPI>
; __device__ __forceinline__ void gemm_tile(const GemmArgs& g, int brow, int bcol, int parity, bool first, bool nvalid, int nbrow, int nbcol) {
;     ...
;     LDA(At, 0, 1); WAIT_V(4); BAR; WAIT_L(0); MMA(1, 0, At, B0); MMA(1, 1, At, B1); BAR; }
;   { LDB(B0, 1, 0); LDA(At, 1, 0); WAIT_V(2); BAR; WAIT_L(0); MMA(0, 0, At, B0); BAR;
;     LDB(B1, 1, 1); WAIT_V(0); BAR; WAIT_L(0); MMA(0, 1, At, B1); BAR; SCHED;
;     LDA(At, 1, 1); BAR; WAIT_L(0); MMA(1, 0, At, B0); MMA(1, 1, At, B1); BAR; }
;   if (wr == 0) BAR;
	s_waitcnt lgkmcnt(0)
	s_setprio 1
	s_waitcnt lgkmcnt(0)
	v_mfma_f32_16x16x32_bf16 v[66:69], v[2:5], v[18:21], v[126:129]
	v_mfma_f32_16x16x32_bf16 v[122:125], v[6:9], v[26:29], v[66:69]
	v_mfma_f32_16x16x32_bf16 v[66:69], v[192:195], v[18:21], v[216:219]
	v_mfma_f32_16x16x32_bf16 v[114:117], v[196:199], v[26:29], v[66:69]
	v_mfma_f32_16x16x32_bf16 v[66:69], v[2:5], v[34:37], v[118:121]
	v_mfma_f32_16x16x32_bf16 v[106:109], v[6:9], v[42:45], v[66:69]
	v_mfma_f32_16x16x32_bf16 v[66:69], v[192:195], v[34:37], v[222:225]
	v_mfma_f32_16x16x32_bf16 v[98:101], v[196:199], v[42:45], v[66:69]
	v_mfma_f32_16x16x32_bf16 v[66:69], v[2:5], v[50:53], v[110:113]
	v_mfma_f32_16x16x32_bf16 v[90:93], v[6:9], v[58:61], v[66:69]
	v_mfma_f32_16x16x32_bf16 v[66:69], v[192:195], v[50:53], v[228:231]
	v_mfma_f32_16x16x32_bf16 v[82:85], v[196:199], v[58:61], v[66:69]
	v_mfma_f32_16x16x32_bf16 v[66:69], v[2:5], v[202:205], v[102:105]
	v_mfma_f32_16x16x32_bf16 v[70:73], v[6:9], v[244:247], v[66:69]
	v_mfma_f32_16x16x32_bf16 v[66:69], v[192:195], v[202:205], v[232:235]
	v_mfma_f32_16x16x32_bf16 v[66:69], v[196:199], v[244:247], v[66:69]
	s_setprio 0
	s_barrier
	ds_read_b128 v[216:219], v148
	ds_read_b128 v[222:225], v148 offset:1024
	ds_read_b128 v[228:231], v148 offset:2048
	ds_read_b128 v[232:235], v148 offset:3072
	s_waitcnt vmcnt(0)
	s_barrier
	s_waitcnt lgkmcnt(0)
	s_setprio 1
	s_waitcnt lgkmcnt(0)
	v_mfma_f32_16x16x32_bf16 v[94:97], v[216:219], v[18:21], v[94:97]
	v_mfma_f32_16x16x32_bf16 v[18:21], v[228:231], v[18:21], v[154:157]
	v_mfma_f32_16x16x32_bf16 v[118:121], v[232:235], v[26:29], v[18:21]
	v_mfma_f32_16x16x32_bf16 v[18:21], v[216:219], v[34:37], v[86:89]
	v_mfma_f32_16x16x32_bf16 v[110:113], v[222:225], v[42:45], v[18:21]
	v_mfma_f32_16x16x32_bf16 v[18:21], v[228:231], v[34:37], v[176:179]
	v_mfma_f32_16x16x32_bf16 v[102:105], v[232:235], v[42:45], v[18:21]
	v_mfma_f32_16x16x32_bf16 v[18:21], v[216:219], v[50:53], v[78:81]
	v_mfma_f32_16x16x32_bf16 v[126:129], v[222:225], v[26:29], v[94:97]
	v_mfma_f32_16x16x32_bf16 v[94:97], v[222:225], v[58:61], v[18:21]
	v_mfma_f32_16x16x32_bf16 v[18:21], v[228:231], v[50:53], v[74:77]
	v_mfma_f32_16x16x32_bf16 v[86:89], v[232:235], v[58:61], v[18:21]
	v_mfma_f32_16x16x32_bf16 v[18:21], v[216:219], v[202:205], v[180:183]
	v_mfma_f32_16x16x32_bf16 v[78:81], v[222:225], v[244:247], v[18:21]
	v_mfma_f32_16x16x32_bf16 v[18:21], v[228:231], v[202:205], v[184:187]
	v_mfma_f32_16x16x32_bf16 v[74:77], v[232:235], v[244:247], v[18:21]
	s_setprio 0
	s_barrier
	ds_read_b128 v[154:157], v147 offset:49152
	ds_read_b128 v[174:177], v147 offset:50176
	ds_read_b128 v[178:181], v146 offset:49152
	ds_read_b128 v[146:149], v146 offset:50176
	ds_read_b128 v[182:185], v145 offset:49152
	ds_read_b128 v[202:205], v145 offset:50176
	ds_read_b128 v[244:247], v144 offset:49152
	ds_read_b128 v[248:251], v144 offset:50176
	s_barrier
	s_waitcnt lgkmcnt(0)
	s_setprio 1
	s_waitcnt lgkmcnt(0)
	v_mfma_f32_16x16x32_bf16 v[18:21], v[2:5], v[154:157], v[62:65]
	v_mfma_f32_16x16x32_bf16 v[58:61], v[6:9], v[174:177], v[18:21]
	v_mfma_f32_16x16x32_bf16 v[18:21], v[192:195], v[154:157], v[206:209]
	v_mfma_f32_16x16x32_bf16 v[50:53], v[196:199], v[174:177], v[18:21]
	v_mfma_f32_16x16x32_bf16 v[18:21], v[2:5], v[178:181], v[54:57]
	v_mfma_f32_16x16x32_bf16 v[42:45], v[6:9], v[146:149], v[18:21]
	v_mfma_f32_16x16x32_bf16 v[18:21], v[192:195], v[178:181], v[236:239]
	v_mfma_f32_16x16x32_bf16 v[34:37], v[196:199], v[146:149], v[18:21]
	v_mfma_f32_16x16x32_bf16 v[18:21], v[2:5], v[182:185], v[46:49]
	v_mfma_f32_16x16x32_bf16 v[2:5], v[2:5], v[244:247], v[38:41]
	v_mfma_f32_16x16x32_bf16 v[26:29], v[6:9], v[202:205], v[18:21]
	v_mfma_f32_16x16x32_bf16 v[18:21], v[192:195], v[182:185], v[240:243]
	v_mfma_f32_16x16x32_bf16 v[6:9], v[6:9], v[248:251], v[2:5]
	v_mfma_f32_16x16x32_bf16 v[2:5], v[192:195], v[244:247], v[150:153]
	v_mfma_f32_16x16x32_bf16 v[18:21], v[196:199], v[202:205], v[18:21]
	v_mfma_f32_16x16x32_bf16 v[2:5], v[196:199], v[248:251], v[2:5]
	s_setprio 0
	s_setprio 1
	v_mfma_f32_16x16x32_bf16 v[22:25], v[216:219], v[178:181], v[22:25]
	v_mfma_f32_16x16x32_bf16 v[30:33], v[216:219], v[154:157], v[30:33]
	v_mfma_f32_16x16x32_bf16 v[46:49], v[222:225], v[146:149], v[22:25]
	v_mfma_f32_16x16x32_bf16 v[22:25], v[228:231], v[178:181], v[166:169]
	v_mfma_f32_16x16x32_bf16 v[10:13], v[228:231], v[182:185], v[10:13]
	v_mfma_f32_16x16x32_bf16 v[62:65], v[222:225], v[174:177], v[30:33]
	v_mfma_f32_16x16x32_bf16 v[30:33], v[228:231], v[154:157], v[162:165]
	v_mfma_f32_16x16x32_bf16 v[38:41], v[232:235], v[146:149], v[22:25]
	v_mfma_f32_16x16x32_bf16 v[14:17], v[216:219], v[182:185], v[14:17]
	v_mfma_f32_16x16x32_bf16 v[22:25], v[232:235], v[202:205], v[10:13]
	v_mfma_f32_16x16x32_bf16 v[10:13], v[216:219], v[244:247], v[170:173]
	v_mfma_f32_16x16x32_bf16 v[54:57], v[232:235], v[174:177], v[30:33]
	v_mfma_f32_16x16x32_bf16 v[30:33], v[222:225], v[202:205], v[14:17]
	v_mfma_f32_16x16x32_bf16 v[14:17], v[222:225], v[248:251], v[10:13]
	v_mfma_f32_16x16x32_bf16 v[10:13], v[228:231], v[244:247], v[188:191]
	v_mfma_f32_16x16x32_bf16 v[10:13], v[232:235], v[248:251], v[10:13]
	s_setprio 0
	s_movk_i32 s0, 0x100
	v_cmp_gt_u32_e32 vcc, s0, v138
	s_barrier
	s_and_saveexec_b64 s[0:1], vcc
	s_cbranch_execz .LBB0_169
	s_barrier

; #define SCHED __builtin_amdgcn_sched_barrier(0)
; template <int EPI>
; __device__ __forceinline__ void gemm_tile(const GemmArgs& g, int brow, int bcol, int parity, bool first, bool nvalid, int nbrow, int nbcol) {
;     ...
;   int rowb_ = brow + wr * 64 + fq * 4; asm volatile("" : "+v"(rowb_));
;   int colb_ = bcol + wc * 32 + fr; asm volatile("" : "+v"(colb_));
;   float* W = (float*)(smem + ((wid < 3) ? (32768 + wid * 9216) : (98304 + (wid - 3) * 9216)));
;   const int wrow0 = rowb_ - fq * 4;
;   const int wcol0 = colb_ - fr;
;   const int lrow0 = wrow0 - brow;
;     ...
;   if constexpr (EPI == EPI_PLAIN) {
;     _Pragma("unroll") for (int ai = 0; ai < 2; ++ai) _Pragma("unroll") for (int bj = 0; bj < 2; ++bj) {
;       SCHED;
;       _Pragma("unroll") for (int m = 0; m < 4; ++m) _Pragma("unroll") for (int j = 0; j < 4; ++j) {
;         const float rs = rstd_s[lrow0 + ai * HALF + m * 16 + fq * 4 + j];
;         _Pragma("unroll") for (int n = 0; n < 2; ++n) W_WRITE(m, n, j, acc[ai][bj][m][n][j] * rs);
;       }
;       bfu* dst = g.outb + (long)(wrow0 + ai * HALF) * g.ldo + g.ocol0 + wcol0 + bj * HALF;
;       W_STORE_BF16(dst, g.ldo);
;     }
.LBB0_610:
	v_mbcnt_lo_u32_b32 v130, -1, 0
	v_mbcnt_hi_u32_b32 v130, -1, v130
	s_add_i32 s21, s21, 1
	s_and_b32 s2, s33, 0x100
	s_add_i32 s2, s2, s14
	v_and_b32_e32 v131, 15, v130
	v_lshrrev_b32_e32 v132, 4, v130
	v_lshl_add_u32 v133, v131, 2, s2
	ds_read_b32 v138, v133
	ds_read_b32 v139, v133 offset:64
	ds_read_b32 v140, v133 offset:128
	ds_read_b32 v141, v133 offset:192
	ds_read_b32 v142, v133 offset:512
	ds_read_b32 v143, v133 offset:576
	ds_read_b32 v144, v133 offset:640
	ds_read_b32 v145, v133 offset:704
	v_lshlrev_b32_e32 v134, 4, v132
	v_lshlrev_b32_e32 v135, 2, v132
	v_and_b32_e32 v134, 16, v134
	v_and_b32_e32 v135, 8, v135
	s_and_b32 s3, s22, 0x7fffff8
	s_lshl_b32 s3, s3, 5
	s_lshr_b32 s12, s33, 1
	s_and_b32 s12, s12, 0x60
	s_add_i32 s3, s3, s12
	v_or_b32_e32 v134, v134, v135
	v_add_lshl_u32 v134, v134, s3, 1
	v_mov_b32_e32 v135, 0
	s_lshr_b32 s12, s33, 2
	s_and_b32 s12, s12, 64
	s_add_i32 s12, s12, s40
	v_add_u32_e32 v136, s12, v131
	s_movk_i32 s3, 0x1c00
	v_mad_u64_u32 v[134:135], vcc, v136, s3, v[134:135]
	v_lshl_add_u64 v[134:135], v[134:135], 0, s[34:35]
	s_mov_b64 s[12:13], 0x1c000
	s_mov_b64 s[14:15], 0x8c000
	s_waitcnt lgkmcnt(0)
	v_pk_mul_f32 v[122:123], v[122:123], v[138:139] op_sel_hi:[1,0]
	v_pk_mul_f32 v[124:125], v[124:125], v[138:139] op_sel_hi:[1,0]
	v_pk_mul_f32 v[126:127], v[126:127], v[138:139] op_sel_hi:[1,0]
	v_pk_mul_f32 v[128:129], v[128:129], v[138:139] op_sel_hi:[1,0]
	v_pk_mul_f32 v[90:91], v[90:91], v[138:139] op_sel_hi:[1,0]
	v_pk_mul_f32 v[92:93], v[92:93], v[138:139] op_sel_hi:[1,0]
	v_pk_mul_f32 v[94:95], v[94:95], v[138:139] op_sel_hi:[1,0]
	v_pk_mul_f32 v[96:97], v[96:97], v[138:139] op_sel_hi:[1,0]
	v_cvt_pk_bf16_f32 v146, v122, v123
	v_cvt_pk_bf16_f32 v147, v124, v125
	v_cvt_pk_bf16_f32 v148, v126, v127
	v_cvt_pk_bf16_f32 v149, v128, v129
	v_cvt_pk_bf16_f32 v150, v90, v91
	v_cvt_pk_bf16_f32 v151, v92, v93
	v_cvt_pk_bf16_f32 v152, v94, v95
	v_cvt_pk_bf16_f32 v153, v96, v97
	v_permlane16_swap_b32_e32 v146, v148
	v_permlane16_swap_b32_e32 v147, v149
	v_permlane16_swap_b32_e32 v150, v152
	v_permlane16_swap_b32_e32 v151, v153
	global_store_dwordx4 v[134:135], v[146:149], off offset:0
	global_store_dwordx4 v[134:135], v[150:153], off offset:256
	v_lshl_add_u64 v[134:135], v[134:135], 0, s[12:13]
	v_pk_mul_f32 v[114:115], v[114:115], v[138:139] op_sel:[0,1] op_sel_hi:[1,1]
	v_pk_mul_f32 v[116:117], v[116:117], v[138:139] op_sel:[0,1] op_sel_hi:[1,1]
	v_pk_mul_f32 v[118:119], v[118:119], v[138:139] op_sel:[0,1] op_sel_hi:[1,1]
	v_pk_mul_f32 v[120:121], v[120:121], v[138:139] op_sel:[0,1] op_sel_hi:[1,1]
	v_pk_mul_f32 v[82:83], v[82:83], v[138:139] op_sel:[0,1] op_sel_hi:[1,1]
	v_pk_mul_f32 v[84:85], v[84:85], v[138:139] op_sel:[0,1] op_sel_hi:[1,1]
	v_pk_mul_f32 v[86:87], v[86:87], v[138:139] op_sel:[0,1] op_sel_hi:[1,1]
	v_pk_mul_f32 v[88:89], v[88:89], v[138:139] op_sel:[0,1] op_sel_hi:[1,1]
	v_cvt_pk_bf16_f32 v154, v114, v115
	v_cvt_pk_bf16_f32 v155, v116, v117
	v_cvt_pk_bf16_f32 v156, v118, v119
	v_cvt_pk_bf16_f32 v157, v120, v121
	v_cvt_pk_bf16_f32 v158, v82, v83
	v_cvt_pk_bf16_f32 v159, v84, v85
	v_cvt_pk_bf16_f32 v160, v86, v87
	v_cvt_pk_bf16_f32 v161, v88, v89
	v_permlane16_swap_b32_e32 v154, v156
	v_permlane16_swap_b32_e32 v155, v157
	v_permlane16_swap_b32_e32 v158, v160
	v_permlane16_swap_b32_e32 v159, v161
	global_store_dwordx4 v[134:135], v[154:157], off offset:0
	global_store_dwordx4 v[134:135], v[158:161], off offset:256
	v_lshl_add_u64 v[134:135], v[134:135], 0, s[12:13]
	v_pk_mul_f32 v[106:107], v[106:107], v[140:141] op_sel_hi:[1,0]
	v_pk_mul_f32 v[108:109], v[108:109], v[140:141] op_sel_hi:[1,0]
	v_pk_mul_f32 v[110:111], v[110:111], v[140:141] op_sel_hi:[1,0]
	v_pk_mul_f32 v[112:113], v[112:113], v[140:141] op_sel_hi:[1,0]
	v_pk_mul_f32 v[74:75], v[74:75], v[140:141] op_sel_hi:[1,0]
	v_pk_mul_f32 v[76:77], v[76:77], v[140:141] op_sel_hi:[1,0]
	v_pk_mul_f32 v[78:79], v[78:79], v[140:141] op_sel_hi:[1,0]
	v_pk_mul_f32 v[80:81], v[80:81], v[140:141] op_sel_hi:[1,0]
	v_cvt_pk_bf16_f32 v146, v106, v107
	v_cvt_pk_bf16_f32 v147, v108, v109
	v_cvt_pk_bf16_f32 v148, v110, v111
	v_cvt_pk_bf16_f32 v149, v112, v113
	v_cvt_pk_bf16_f32 v150, v74, v75
	v_cvt_pk_bf16_f32 v151, v76, v77
	v_cvt_pk_bf16_f32 v152, v78, v79
	v_cvt_pk_bf16_f32 v153, v80, v81
	v_permlane16_swap_b32_e32 v146, v148
	v_permlane16_swap_b32_e32 v147, v149
	v_permlane16_swap_b32_e32 v150, v152
	v_permlane16_swap_b32_e32 v151, v153
	global_store_dwordx4 v[134:135], v[146:149], off offset:0
	global_store_dwordx4 v[134:135], v[150:153], off offset:256
	v_lshl_add_u64 v[134:135], v[134:135], 0, s[12:13]
	v_pk_mul_f32 v[98:99], v[98:99], v[140:141] op_sel:[0,1] op_sel_hi:[1,1]
	v_pk_mul_f32 v[100:101], v[100:101], v[140:141] op_sel:[0,1] op_sel_hi:[1,1]
	v_pk_mul_f32 v[102:103], v[102:103], v[140:141] op_sel:[0,1] op_sel_hi:[1,1]
	v_pk_mul_f32 v[104:105], v[104:105], v[140:141] op_sel:[0,1] op_sel_hi:[1,1]
	v_pk_mul_f32 v[66:67], v[66:67], v[140:141] op_sel:[0,1] op_sel_hi:[1,1]
	v_pk_mul_f32 v[68:69], v[68:69], v[140:141] op_sel:[0,1] op_sel_hi:[1,1]
	v_pk_mul_f32 v[70:71], v[70:71], v[140:141] op_sel:[0,1] op_sel_hi:[1,1]
; #define SCHED __builtin_amdgcn_sched_barrier(0)
; template <int EPI>
; __device__ __forceinline__ void gemm_tile(const GemmArgs& g, int brow, int bcol, int parity, bool first, bool nvalid, int nbrow, int nbcol) {
;     ...
;   if constexpr (EPI == EPI_PLAIN) {
;     _Pragma("unroll") for (int ai = 0; ai < 2; ++ai) _Pragma("unroll") for (int bj = 0; bj < 2; ++bj) {
;       SCHED;
;       _Pragma("unroll") for (int m = 0; m < 4; ++m) _Pragma("unroll") for (int j = 0; j < 4; ++j) {
;         const float rs = rstd_s[lrow0 + ai * HALF + m * 16 + fq * 4 + j];
;         _Pragma("unroll") for (int n = 0; n < 2; ++n) W_WRITE(m, n, j, acc[ai][bj][m][n][j] * rs);
;       }
;       bfu* dst = g.outb + (long)(wrow0 + ai * HALF) * g.ldo + g.ocol0 + wcol0 + bj * HALF;
;       W_STORE_BF16(dst, g.ldo);
;     }
	v_pk_mul_f32 v[72:73], v[72:73], v[140:141] op_sel:[0,1] op_sel_hi:[1,1]
	v_cvt_pk_bf16_f32 v154, v98, v99
	v_cvt_pk_bf16_f32 v155, v100, v101
	v_cvt_pk_bf16_f32 v156, v102, v103
	v_cvt_pk_bf16_f32 v157, v104, v105
	v_cvt_pk_bf16_f32 v158, v66, v67
	v_cvt_pk_bf16_f32 v159, v68, v69
	v_cvt_pk_bf16_f32 v160, v70, v71
	v_cvt_pk_bf16_f32 v161, v72, v73
	v_permlane16_swap_b32_e32 v154, v156
	v_permlane16_swap_b32_e32 v155, v157
	v_permlane16_swap_b32_e32 v158, v160
	v_permlane16_swap_b32_e32 v159, v161
	global_store_dwordx4 v[134:135], v[154:157], off offset:0
	global_store_dwordx4 v[134:135], v[158:161], off offset:256
	v_lshl_add_u64 v[134:135], v[134:135], 0, s[14:15]
	v_pk_mul_f32 v[58:59], v[58:59], v[142:143] op_sel_hi:[1,0]
	v_pk_mul_f32 v[60:61], v[60:61], v[142:143] op_sel_hi:[1,0]
	v_pk_mul_f32 v[62:63], v[62:63], v[142:143] op_sel_hi:[1,0]
	v_pk_mul_f32 v[64:65], v[64:65], v[142:143] op_sel_hi:[1,0]
	v_pk_mul_f32 v[26:27], v[26:27], v[142:143] op_sel_hi:[1,0]
	v_pk_mul_f32 v[28:29], v[28:29], v[142:143] op_sel_hi:[1,0]
	v_pk_mul_f32 v[30:31], v[30:31], v[142:143] op_sel_hi:[1,0]
	v_pk_mul_f32 v[32:33], v[32:33], v[142:143] op_sel_hi:[1,0]
	v_cvt_pk_bf16_f32 v146, v58, v59
	v_cvt_pk_bf16_f32 v147, v60, v61
	v_cvt_pk_bf16_f32 v148, v62, v63
	v_cvt_pk_bf16_f32 v149, v64, v65
	v_cvt_pk_bf16_f32 v150, v26, v27
	v_cvt_pk_bf16_f32 v151, v28, v29
	v_cvt_pk_bf16_f32 v152, v30, v31
	v_cvt_pk_bf16_f32 v153, v32, v33
	v_permlane16_swap_b32_e32 v146, v148
	v_permlane16_swap_b32_e32 v147, v149
	v_permlane16_swap_b32_e32 v150, v152
	v_permlane16_swap_b32_e32 v151, v153
	global_store_dwordx4 v[134:135], v[146:149], off offset:0
	global_store_dwordx4 v[134:135], v[150:153], off offset:256
	v_lshl_add_u64 v[134:135], v[134:135], 0, s[12:13]
	v_pk_mul_f32 v[50:51], v[50:51], v[142:143] op_sel:[0,1] op_sel_hi:[1,1]
	v_pk_mul_f32 v[52:53], v[52:53], v[142:143] op_sel:[0,1] op_sel_hi:[1,1]
	v_pk_mul_f32 v[54:55], v[54:55], v[142:143] op_sel:[0,1] op_sel_hi:[1,1]
	v_pk_mul_f32 v[56:57], v[56:57], v[142:143] op_sel:[0,1] op_sel_hi:[1,1]
	v_pk_mul_f32 v[18:19], v[18:19], v[142:143] op_sel:[0,1] op_sel_hi:[1,1]
	v_pk_mul_f32 v[20:21], v[20:21], v[142:143] op_sel:[0,1] op_sel_hi:[1,1]
	v_pk_mul_f32 v[22:23], v[22:23], v[142:143] op_sel:[0,1] op_sel_hi:[1,1]
	v_pk_mul_f32 v[24:25], v[24:25], v[142:143] op_sel:[0,1] op_sel_hi:[1,1]
	v_cvt_pk_bf16_f32 v154, v50, v51
	v_cvt_pk_bf16_f32 v155, v52, v53
	v_cvt_pk_bf16_f32 v156, v54, v55
	v_cvt_pk_bf16_f32 v157, v56, v57
	v_cvt_pk_bf16_f32 v158, v18, v19
	v_cvt_pk_bf16_f32 v159, v20, v21
	v_cvt_pk_bf16_f32 v160, v22, v23
	v_cvt_pk_bf16_f32 v161, v24, v25
	v_permlane16_swap_b32_e32 v154, v156
	v_permlane16_swap_b32_e32 v155, v157
	v_permlane16_swap_b32_e32 v158, v160
	v_permlane16_swap_b32_e32 v159, v161
	global_store_dwordx4 v[134:135], v[154:157], off offset:0
	global_store_dwordx4 v[134:135], v[158:161], off offset:256
	v_lshl_add_u64 v[134:135], v[134:135], 0, s[12:13]
	v_pk_mul_f32 v[42:43], v[42:43], v[144:145] op_sel_hi:[1,0]
	v_pk_mul_f32 v[44:45], v[44:45], v[144:145] op_sel_hi:[1,0]
	v_pk_mul_f32 v[46:47], v[46:47], v[144:145] op_sel_hi:[1,0]
	v_pk_mul_f32 v[48:49], v[48:49], v[144:145] op_sel_hi:[1,0]
	v_pk_mul_f32 v[10:11], v[10:11], v[144:145] op_sel_hi:[1,0]
	v_pk_mul_f32 v[12:13], v[12:13], v[144:145] op_sel_hi:[1,0]
	v_pk_mul_f32 v[14:15], v[14:15], v[144:145] op_sel_hi:[1,0]
	v_pk_mul_f32 v[16:17], v[16:17], v[144:145] op_sel_hi:[1,0]
	v_cvt_pk_bf16_f32 v146, v42, v43
	v_cvt_pk_bf16_f32 v147, v44, v45
	v_cvt_pk_bf16_f32 v148, v46, v47
	v_cvt_pk_bf16_f32 v149, v48, v49
	v_cvt_pk_bf16_f32 v150, v10, v11
	v_cvt_pk_bf16_f32 v151, v12, v13
	v_cvt_pk_bf16_f32 v152, v14, v15
	v_cvt_pk_bf16_f32 v153, v16, v17
	v_permlane16_swap_b32_e32 v146, v148
	v_permlane16_swap_b32_e32 v147, v149
	v_permlane16_swap_b32_e32 v150, v152
	v_permlane16_swap_b32_e32 v151, v153
	global_store_dwordx4 v[134:135], v[146:149], off offset:0
	global_store_dwordx4 v[134:135], v[150:153], off offset:256
	v_lshl_add_u64 v[134:135], v[134:135], 0, s[12:13]
	v_pk_mul_f32 v[34:35], v[34:35], v[144:145] op_sel:[0,1] op_sel_hi:[1,1]
	v_pk_mul_f32 v[36:37], v[36:37], v[144:145] op_sel:[0,1] op_sel_hi:[1,1]
	v_pk_mul_f32 v[38:39], v[38:39], v[144:145] op_sel:[0,1] op_sel_hi:[1,1]
	v_pk_mul_f32 v[40:41], v[40:41], v[144:145] op_sel:[0,1] op_sel_hi:[1,1]
	v_pk_mul_f32 v[2:3], v[2:3], v[144:145] op_sel:[0,1] op_sel_hi:[1,1]
	v_pk_mul_f32 v[4:5], v[4:5], v[144:145] op_sel:[0,1] op_sel_hi:[1,1]
	v_pk_mul_f32 v[6:7], v[6:7], v[144:145] op_sel:[0,1] op_sel_hi:[1,1]
	v_pk_mul_f32 v[8:9], v[8:9], v[144:145] op_sel:[0,1] op_sel_hi:[1,1]
	v_cvt_pk_bf16_f32 v154, v34, v35
	v_cvt_pk_bf16_f32 v155, v36, v37
	v_cvt_pk_bf16_f32 v156, v38, v39
	v_cvt_pk_bf16_f32 v157, v40, v41
	v_cvt_pk_bf16_f32 v158, v2, v3
	v_cvt_pk_bf16_f32 v159, v4, v5
	v_cvt_pk_bf16_f32 v160, v6, v7
	v_cvt_pk_bf16_f32 v161, v8, v9
	v_permlane16_swap_b32_e32 v154, v156
	v_permlane16_swap_b32_e32 v155, v157
	v_permlane16_swap_b32_e32 v158, v160
	v_permlane16_swap_b32_e32 v159, v161
	global_store_dwordx4 v[134:135], v[154:157], off offset:0
	global_store_dwordx4 v[134:135], v[158:161], off offset:256

; #define STAGE_B(P, br, kt) do { const char* _gb = (const char*)(Bt + ((long)(br) * K + (long)(kt) * BK)); \
;     __builtin_amdgcn_global_load_lds((const unsigned*)(_gb + bofl0), (unsigned*)((char*)(P) + gtid_ * 16), 16, 0, 0); \
;     __builtin_amdgcn_global_load_lds((const unsigned*)(_gb + (long)K * 128 + bofl0), (unsigned*)((char*)(P) + gtid_ * 16 + 8192), 16, 0, 0); } while (0)
; #define LDA(dst, b, h) for (int m = 0; m < 4; ++m) for (int k = 0; k < 2; ++k) \
;     dst[m][k] = *reinterpret_cast<const bf16x8*>((char*)SA(b, h) + lds_byte(wr * 64 + m * 16 + fr, k * 32 + fq * 8))
; #define LDB(dst, b, h) for (int n = 0; n < 2; ++n) for (int k = 0; k < 2; ++k) \
;     dst[n][k] = *reinterpret_cast<const bf16x8*>((char*)SB(b, h) + lds_byte(wc * 32 + n * 16 + fr, k * 32 + fq * 8))
; #define MMA(ai, bj, At_, Bt_) do { __builtin_amdgcn_s_setprio(1); \
;     for (int m = 0; m < 4; ++m) for (int n = 0; n < 2; ++n) for (int k = 0; k < 2; ++k) \
;       acc[ai][bj][m][n] = __builtin_amdgcn_mfma_f32_16x16x32_bf16(At_[m][k], Bt_[n][k], acc[ai][bj][m][n], 0, 0, 0); \
;     __builtin_amdgcn_s_setprio(0); } while (0)
; #define WAIT_V(n) asm volatile("s_waitcnt vmcnt(" #n ")" ::: "memory")
; #define WAIT_L(n) asm volatile("s_waitcnt lgkmcnt(" #n ")" ::: "memory")
; #define BAR __builtin_amdgcn_s_barrier()
; #define SCHED __builtin_amdgcn_sched_barrier(0)
; template <int EPI>
; __device__ __forceinline__ void gemm_tile(const GemmArgs& g, int brow, int bcol, int parity, bool first, bool nvalid, int nbrow, int nbcol) {
;     ...
;     LDB(B0, 0, 0); SCHED; LDA(At, 0, 0); STAGE_A(SA(1, 1), brow + HALF, t + 1);
;     WAIT_L(8); BAR; WAIT_L(0); MMA(0, 0, At, B0); BAR; SCHED;
;     LDB(B1, 0, 1); STAGE_B(SB(0, 0), bcol, t + 2);
;     BAR; WAIT_L(0); MMA(0, 1, At, B1); BAR; SCHED;
;     LDA(At, 0, 1); STAGE_A(SA(0, 0), brow, t + 2);
;     BAR; WAIT_L(0); MMA(1, 0, At, B0); BAR; SCHED;
;     STAGE_B(SB(0, 1), bcol + HALF, t + 2);
;     WAIT_V(6); BAR; MMA(1, 1, At, B1); BAR; SCHED;
.LBB0_640:
	ds_read_b128 v[164:167], v157
	ds_read_b128 v[168:171], v157 offset:1024
	ds_read_b128 v[172:175], v157 offset:2048
	ds_read_b128 v[176:179], v157 offset:3072
	v_add_u32_e32 v161, 0xc000, v137
	v_lshl_add_u64 v[210:211], s[12:13], 0, v[130:131]
	v_readfirstlane_b32 s2, v161
	v_add_u32_e32 v162, 0xe000, v137
	v_lshl_add_u64 v[158:159], v[210:211], 0, s[24:25]
	s_mov_b32 m0, s2
	v_readfirstlane_b32 s2, v162
	ds_read_b128 v[180:183], v147
	ds_read_b128 v[184:187], v147 offset:1024
	ds_read_b128 v[188:191], v146
	ds_read_b128 v[192:195], v146 offset:1024
	ds_read_b128 v[196:199], v145
	ds_read_b128 v[202:205], v145 offset:1024
	ds_read_b128 v[206:209], v144
	ds_read_b128 v[216:219], v144 offset:1024
	global_load_lds_dwordx4 v[158:159], off
	v_lshl_add_u64 v[158:159], v[210:211], 0, s[36:37]
	s_mov_b32 m0, s2
	s_nop 0
	global_load_lds_dwordx4 v[158:159], off
	s_waitcnt lgkmcnt(8)
	s_barrier
	s_waitcnt lgkmcnt(0)
	s_setprio 1
	s_waitcnt lgkmcnt(0)
	v_mfma_f32_16x16x32_bf16 v[126:129], v[164:167], v[180:183], v[126:129]
	v_mfma_f32_16x16x32_bf16 v[122:125], v[172:175], v[180:183], v[122:125]
	v_mfma_f32_16x16x32_bf16 v[118:121], v[164:167], v[188:191], v[118:121]
	v_mfma_f32_16x16x32_bf16 v[114:117], v[172:175], v[188:191], v[114:117]
	v_mfma_f32_16x16x32_bf16 v[110:113], v[164:167], v[196:199], v[110:113]
	v_mfma_f32_16x16x32_bf16 v[106:109], v[172:175], v[196:199], v[106:109]
	v_mfma_f32_16x16x32_bf16 v[102:105], v[164:167], v[206:209], v[102:105]
	v_mfma_f32_16x16x32_bf16 v[98:101], v[172:175], v[206:209], v[98:101]
	v_mfma_f32_16x16x32_bf16 v[126:129], v[168:171], v[184:187], v[126:129]
	v_mfma_f32_16x16x32_bf16 v[122:125], v[176:179], v[184:187], v[122:125]
	v_mfma_f32_16x16x32_bf16 v[118:121], v[168:171], v[192:195], v[118:121]
	v_mfma_f32_16x16x32_bf16 v[114:117], v[176:179], v[192:195], v[114:117]
	v_mfma_f32_16x16x32_bf16 v[110:113], v[168:171], v[202:205], v[110:113]
	v_mfma_f32_16x16x32_bf16 v[106:109], v[176:179], v[202:205], v[106:109]
	v_mfma_f32_16x16x32_bf16 v[102:105], v[168:171], v[216:219], v[102:105]
	v_mfma_f32_16x16x32_bf16 v[98:101], v[176:179], v[216:219], v[98:101]
	s_setprio 0
	s_barrier
	v_add_u32_e32 v158, s15, v142
	v_lshl_add_u64 v[212:213], s[0:1], 0, v[130:131]
	v_readfirstlane_b32 s2, v158
	v_add_u32_e32 v159, 0x2000, v158
	v_lshl_add_u64 v[222:223], v[212:213], 0, s[78:79]
	s_mov_b32 m0, s2
	v_readfirstlane_b32 s2, v159
	ds_read_b128 v[228:231], v154
	ds_read_b128 v[232:235], v154 offset:1024
	ds_read_b128 v[236:239], v154 offset:2048
	ds_read_b128 v[240:243], v154 offset:3072
	global_load_lds_dwordx4 v[222:223], off
	v_lshl_add_u64 v[222:223], v[212:213], 0, s[66:67]
	s_mov_b32 m0, s2
	s_nop 0
	global_load_lds_dwordx4 v[222:223], off
	s_barrier
	s_waitcnt lgkmcnt(0)
	s_setprio 1
	s_waitcnt lgkmcnt(0)
	v_mfma_f32_16x16x32_bf16 v[94:97], v[228:231], v[180:183], v[94:97]
	v_mfma_f32_16x16x32_bf16 v[90:93], v[236:239], v[180:183], v[90:93]
	v_mfma_f32_16x16x32_bf16 v[86:89], v[228:231], v[188:191], v[86:89]
	v_mfma_f32_16x16x32_bf16 v[82:85], v[236:239], v[188:191], v[82:85]
	v_mfma_f32_16x16x32_bf16 v[78:81], v[228:231], v[196:199], v[78:81]
	v_mfma_f32_16x16x32_bf16 v[74:77], v[236:239], v[196:199], v[74:77]
	v_mfma_f32_16x16x32_bf16 v[70:73], v[228:231], v[206:209], v[70:73]
	v_mfma_f32_16x16x32_bf16 v[66:69], v[236:239], v[206:209], v[66:69]
	v_mfma_f32_16x16x32_bf16 v[94:97], v[232:235], v[184:187], v[94:97]
	v_mfma_f32_16x16x32_bf16 v[90:93], v[240:243], v[184:187], v[90:93]
	v_mfma_f32_16x16x32_bf16 v[86:89], v[232:235], v[192:195], v[86:89]
	v_mfma_f32_16x16x32_bf16 v[82:85], v[240:243], v[192:195], v[82:85]
	v_mfma_f32_16x16x32_bf16 v[78:81], v[232:235], v[202:205], v[78:81]
	v_mfma_f32_16x16x32_bf16 v[74:77], v[240:243], v[202:205], v[74:77]
	v_mfma_f32_16x16x32_bf16 v[70:73], v[232:235], v[216:219], v[70:73]
	v_mfma_f32_16x16x32_bf16 v[66:69], v[240:243], v[216:219], v[66:69]
	s_setprio 0
	s_barrier
	v_readfirstlane_b32 s2, v137
	v_lshl_add_u64 v[222:223], v[210:211], 0, s[38:39]
	s_mov_b32 m0, s2
	v_readfirstlane_b32 s2, v136
	ds_read_b128 v[180:183], v147 offset:16384
	ds_read_b128 v[184:187], v147 offset:17408
	ds_read_b128 v[188:191], v146 offset:16384
	ds_read_b128 v[192:195], v146 offset:17408
	ds_read_b128 v[196:199], v145 offset:16384
	ds_read_b128 v[202:205], v145 offset:17408
	ds_read_b128 v[206:209], v144 offset:16384
	ds_read_b128 v[216:219], v144 offset:17408
	global_load_lds_dwordx4 v[222:223], off
	v_lshl_add_u64 v[222:223], v[210:211], 0, s[42:43]
	s_mov_b32 m0, s2
	s_nop 0
	global_load_lds_dwordx4 v[222:223], off
	s_barrier
	s_waitcnt lgkmcnt(0)
	s_setprio 1
	s_waitcnt lgkmcnt(0)
	v_mfma_f32_16x16x32_bf16 v[62:65], v[164:167], v[180:183], v[62:65]
	v_mfma_f32_16x16x32_bf16 v[58:61], v[172:175], v[180:183], v[58:61]
	v_mfma_f32_16x16x32_bf16 v[54:57], v[164:167], v[188:191], v[54:57]
	v_mfma_f32_16x16x32_bf16 v[50:53], v[172:175], v[188:191], v[50:53]
	v_mfma_f32_16x16x32_bf16 v[46:49], v[164:167], v[196:199], v[46:49]
	v_mfma_f32_16x16x32_bf16 v[42:45], v[172:175], v[196:199], v[42:45]
	v_mfma_f32_16x16x32_bf16 v[38:41], v[164:167], v[206:209], v[38:41]
	v_mfma_f32_16x16x32_bf16 v[34:37], v[172:175], v[206:209], v[34:37]
	v_mfma_f32_16x16x32_bf16 v[62:65], v[168:171], v[184:187], v[62:65]
	v_mfma_f32_16x16x32_bf16 v[58:61], v[176:179], v[184:187], v[58:61]
	v_mfma_f32_16x16x32_bf16 v[54:57], v[168:171], v[192:195], v[54:57]
	v_mfma_f32_16x16x32_bf16 v[50:53], v[176:179], v[192:195], v[50:53]
	v_mfma_f32_16x16x32_bf16 v[46:49], v[168:171], v[202:205], v[46:49]
	v_mfma_f32_16x16x32_bf16 v[42:45], v[176:179], v[202:205], v[42:45]
	v_mfma_f32_16x16x32_bf16 v[38:41], v[168:171], v[216:219], v[38:41]
	v_mfma_f32_16x16x32_bf16 v[34:37], v[176:179], v[216:219], v[34:37]
	s_setprio 0
	s_barrier
; #define STAGE_B(P, br, kt) do { const char* _gb = (const char*)(Bt + ((long)(br) * K + (long)(kt) * BK)); \
;     __builtin_amdgcn_global_load_lds((const unsigned*)(_gb + bofl0), (unsigned*)((char*)(P) + gtid_ * 16), 16, 0, 0); \
;     __builtin_amdgcn_global_load_lds((const unsigned*)(_gb + (long)K * 128 + bofl0), (unsigned*)((char*)(P) + gtid_ * 16 + 8192), 16, 0, 0); } while (0)
; #define LDA(dst, b, h) for (int m = 0; m < 4; ++m) for (int k = 0; k < 2; ++k) \
;     dst[m][k] = *reinterpret_cast<const bf16x8*>((char*)SA(b, h) + lds_byte(wr * 64 + m * 16 + fr, k * 32 + fq * 8))
; #define LDB(dst, b, h) for (int n = 0; n < 2; ++n) for (int k = 0; k < 2; ++k) \
;     dst[n][k] = *reinterpret_cast<const bf16x8*>((char*)SB(b, h) + lds_byte(wc * 32 + n * 16 + fr, k * 32 + fq * 8))
; #define MMA(ai, bj, At_, Bt_) do { __builtin_amdgcn_s_setprio(1); \
;     for (int m = 0; m < 4; ++m) for (int n = 0; n < 2; ++n) for (int k = 0; k < 2; ++k) \
;       acc[ai][bj][m][n] = __builtin_amdgcn_mfma_f32_16x16x32_bf16(At_[m][k], Bt_[n][k], acc[ai][bj][m][n], 0, 0, 0); \
;     __builtin_amdgcn_s_setprio(0); } while (0)
; #define WAIT_V(n) asm volatile("s_waitcnt vmcnt(" #n ")" ::: "memory")
; #define WAIT_L(n) asm volatile("s_waitcnt lgkmcnt(" #n ")" ::: "memory")
; #define BAR __builtin_amdgcn_s_barrier()
; #define SCHED __builtin_amdgcn_sched_barrier(0)
; template <int EPI>
; __device__ __forceinline__ void gemm_tile(const GemmArgs& g, int brow, int bcol, int parity, bool first, bool nvalid, int nbrow, int nbcol) {
;     ...
;     STAGE_B(SB(0, 1), bcol + HALF, t + 2);
;     WAIT_V(6); BAR; MMA(1, 1, At, B1); BAR; SCHED;
;     LDB(B0, 1, 0); SCHED; LDA(At, 1, 0); STAGE_A(SA(0, 1), brow + HALF, t + 2);
;     WAIT_L(8); BAR; WAIT_L(0); MMA(0, 0, At, B0); BAR; SCHED;
;     LDB(B1, 1, 1); STAGE_B(SB(1, 0), bcol, t + 3);
;     BAR; WAIT_L(0); MMA(0, 1, At, B1); BAR; SCHED;
;     LDA(At, 1, 1); STAGE_A(SA(1, 0), brow, t + 3);
;     BAR; WAIT_L(0); MMA(1, 0, At, B0); BAR; SCHED;
	v_readfirstlane_b32 s2, v135
	v_add_u32_e32 v160, 0x2000, v135
	v_lshl_add_u64 v[164:165], v[212:213], 0, s[76:77]
	s_mov_b32 m0, s2
	v_readfirstlane_b32 s2, v160
	global_load_lds_dwordx4 v[164:165], off
	v_lshl_add_u64 v[164:165], v[212:213], 0, s[96:97]
	s_mov_b32 m0, s2
	s_nop 0
	global_load_lds_dwordx4 v[164:165], off
	s_waitcnt vmcnt(6)
	s_barrier
	s_setprio 1
	v_mfma_f32_16x16x32_bf16 v[30:33], v[228:231], v[180:183], v[30:33]
	v_mfma_f32_16x16x32_bf16 v[26:29], v[236:239], v[180:183], v[26:29]
	v_mfma_f32_16x16x32_bf16 v[22:25], v[228:231], v[188:191], v[22:25]
	v_mfma_f32_16x16x32_bf16 v[18:21], v[236:239], v[188:191], v[18:21]
	v_mfma_f32_16x16x32_bf16 v[14:17], v[228:231], v[196:199], v[14:17]
	v_mfma_f32_16x16x32_bf16 v[10:13], v[236:239], v[196:199], v[10:13]
	v_mfma_f32_16x16x32_bf16 v[6:9], v[228:231], v[206:209], v[6:9]
	v_mfma_f32_16x16x32_bf16 v[2:5], v[236:239], v[206:209], v[2:5]
	v_mfma_f32_16x16x32_bf16 v[30:33], v[232:235], v[184:187], v[30:33]
	v_mfma_f32_16x16x32_bf16 v[26:29], v[240:243], v[184:187], v[26:29]
	v_mfma_f32_16x16x32_bf16 v[22:25], v[232:235], v[192:195], v[22:25]
	v_mfma_f32_16x16x32_bf16 v[18:21], v[240:243], v[192:195], v[18:21]
	v_mfma_f32_16x16x32_bf16 v[14:17], v[232:235], v[202:205], v[14:17]
	v_mfma_f32_16x16x32_bf16 v[10:13], v[240:243], v[202:205], v[10:13]
	v_mfma_f32_16x16x32_bf16 v[6:9], v[232:235], v[216:219], v[6:9]
	v_mfma_f32_16x16x32_bf16 v[2:5], v[240:243], v[216:219], v[2:5]
	s_setprio 0
	s_barrier
	ds_read_b128 v[164:167], v149
	ds_read_b128 v[168:171], v149 offset:1024
	ds_read_b128 v[172:175], v149 offset:2048
	ds_read_b128 v[176:179], v149 offset:3072
	v_readfirstlane_b32 s2, v134
	v_lshl_add_u64 v[222:223], v[210:211], 0, s[44:45]
	s_mov_b32 m0, s2
	v_readfirstlane_b32 s2, v133
	ds_read_b128 v[180:183], v147 offset:32768
	ds_read_b128 v[184:187], v147 offset:33792
	ds_read_b128 v[188:191], v146 offset:32768
	ds_read_b128 v[192:195], v146 offset:33792
	ds_read_b128 v[196:199], v145 offset:32768
	ds_read_b128 v[202:205], v145 offset:33792
	ds_read_b128 v[206:209], v144 offset:32768
	ds_read_b128 v[216:219], v144 offset:33792
	global_load_lds_dwordx4 v[222:223], off
	v_lshl_add_u64 v[222:223], v[210:211], 0, s[46:47]
	s_mov_b32 m0, s2
	s_nop 0
	global_load_lds_dwordx4 v[222:223], off
	s_waitcnt lgkmcnt(8)
	s_barrier
	s_waitcnt lgkmcnt(0)
	s_setprio 1
	s_waitcnt lgkmcnt(0)
	v_mfma_f32_16x16x32_bf16 v[126:129], v[164:167], v[180:183], v[126:129]
	v_mfma_f32_16x16x32_bf16 v[122:125], v[172:175], v[180:183], v[122:125]
	v_mfma_f32_16x16x32_bf16 v[118:121], v[164:167], v[188:191], v[118:121]
	v_mfma_f32_16x16x32_bf16 v[114:117], v[172:175], v[188:191], v[114:117]
	v_mfma_f32_16x16x32_bf16 v[110:113], v[164:167], v[196:199], v[110:113]
	v_mfma_f32_16x16x32_bf16 v[106:109], v[172:175], v[196:199], v[106:109]
	v_mfma_f32_16x16x32_bf16 v[102:105], v[164:167], v[206:209], v[102:105]
	v_mfma_f32_16x16x32_bf16 v[98:101], v[172:175], v[206:209], v[98:101]
	v_mfma_f32_16x16x32_bf16 v[126:129], v[168:171], v[184:187], v[126:129]
	v_mfma_f32_16x16x32_bf16 v[122:125], v[176:179], v[184:187], v[122:125]
	v_mfma_f32_16x16x32_bf16 v[118:121], v[168:171], v[192:195], v[118:121]
	v_mfma_f32_16x16x32_bf16 v[114:117], v[176:179], v[192:195], v[114:117]
	v_mfma_f32_16x16x32_bf16 v[110:113], v[168:171], v[202:205], v[110:113]
	v_mfma_f32_16x16x32_bf16 v[106:109], v[176:179], v[202:205], v[106:109]
	v_mfma_f32_16x16x32_bf16 v[102:105], v[168:171], v[216:219], v[102:105]
	v_mfma_f32_16x16x32_bf16 v[98:101], v[176:179], v[216:219], v[98:101]
	s_setprio 0
	s_barrier
	v_readfirstlane_b32 s2, v150
	v_lshl_add_u64 v[222:223], v[212:213], 0, s[58:59]
	s_mov_b32 m0, s2
	v_readfirstlane_b32 s2, v151
	ds_read_b128 v[228:231], v148
	ds_read_b128 v[232:235], v148 offset:1024
	ds_read_b128 v[236:239], v148 offset:2048
	ds_read_b128 v[240:243], v148 offset:3072
	global_load_lds_dwordx4 v[222:223], off
	v_lshl_add_u64 v[222:223], v[212:213], 0, vcc
	s_mov_b32 m0, s2
	s_nop 0
	global_load_lds_dwordx4 v[222:223], off
	s_barrier
	s_waitcnt lgkmcnt(0)
	s_setprio 1
	s_waitcnt lgkmcnt(0)
	v_mfma_f32_16x16x32_bf16 v[94:97], v[228:231], v[180:183], v[94:97]
	v_mfma_f32_16x16x32_bf16 v[90:93], v[236:239], v[180:183], v[90:93]
	v_mfma_f32_16x16x32_bf16 v[86:89], v[228:231], v[188:191], v[86:89]
	v_mfma_f32_16x16x32_bf16 v[82:85], v[236:239], v[188:191], v[82:85]
	v_mfma_f32_16x16x32_bf16 v[78:81], v[228:231], v[196:199], v[78:81]
	v_mfma_f32_16x16x32_bf16 v[74:77], v[236:239], v[196:199], v[74:77]
	v_mfma_f32_16x16x32_bf16 v[70:73], v[228:231], v[206:209], v[70:73]
	v_mfma_f32_16x16x32_bf16 v[66:69], v[236:239], v[206:209], v[66:69]
	v_mfma_f32_16x16x32_bf16 v[94:97], v[232:235], v[184:187], v[94:97]
	v_mfma_f32_16x16x32_bf16 v[90:93], v[240:243], v[184:187], v[90:93]
	v_mfma_f32_16x16x32_bf16 v[86:89], v[232:235], v[192:195], v[86:89]
	v_mfma_f32_16x16x32_bf16 v[82:85], v[240:243], v[192:195], v[82:85]
	v_mfma_f32_16x16x32_bf16 v[78:81], v[232:235], v[202:205], v[78:81]
	v_mfma_f32_16x16x32_bf16 v[74:77], v[240:243], v[202:205], v[74:77]
	v_mfma_f32_16x16x32_bf16 v[70:73], v[232:235], v[216:219], v[70:73]
	v_mfma_f32_16x16x32_bf16 v[66:69], v[240:243], v[216:219], v[66:69]
	s_setprio 0
	s_barrier
	v_readfirstlane_b32 s2, v152
	v_lshl_add_u64 v[222:223], v[210:211], 0, s[48:49]
	s_mov_b32 m0, s2
	v_readfirstlane_b32 s2, v153
	ds_read_b128 v[180:183], v147 offset:49152
	ds_read_b128 v[184:187], v147 offset:50176
	ds_read_b128 v[188:191], v146 offset:49152
	ds_read_b128 v[192:195], v146 offset:50176
	ds_read_b128 v[196:199], v145 offset:49152
	ds_read_b128 v[202:205], v145 offset:50176
	ds_read_b128 v[206:209], v144 offset:49152
	ds_read_b128 v[216:219], v144 offset:50176
	global_load_lds_dwordx4 v[222:223], off
	v_lshl_add_u64 v[210:211], v[210:211], 0, s[50:51]
	s_mov_b32 m0, s2
	s_nop 0
	global_load_lds_dwordx4 v[210:211], off
	s_barrier
; #define STAGE_B(P, br, kt) do { const char* _gb = (const char*)(Bt + ((long)(br) * K + (long)(kt) * BK)); \
;     __builtin_amdgcn_global_load_lds((const unsigned*)(_gb + bofl0), (unsigned*)((char*)(P) + gtid_ * 16), 16, 0, 0); \
;     __builtin_amdgcn_global_load_lds((const unsigned*)(_gb + (long)K * 128 + bofl0), (unsigned*)((char*)(P) + gtid_ * 16 + 8192), 16, 0, 0); } while (0)
; #define LDA(dst, b, h) for (int m = 0; m < 4; ++m) for (int k = 0; k < 2; ++k) \
;     dst[m][k] = *reinterpret_cast<const bf16x8*>((char*)SA(b, h) + lds_byte(wr * 64 + m * 16 + fr, k * 32 + fq * 8))
; #define LDB(dst, b, h) for (int n = 0; n < 2; ++n) for (int k = 0; k < 2; ++k) \
;     dst[n][k] = *reinterpret_cast<const bf16x8*>((char*)SB(b, h) + lds_byte(wc * 32 + n * 16 + fr, k * 32 + fq * 8))
; #define MMA(ai, bj, At_, Bt_) do { __builtin_amdgcn_s_setprio(1); \
;     for (int m = 0; m < 4; ++m) for (int n = 0; n < 2; ++n) for (int k = 0; k < 2; ++k) \
;       acc[ai][bj][m][n] = __builtin_amdgcn_mfma_f32_16x16x32_bf16(At_[m][k], Bt_[n][k], acc[ai][bj][m][n], 0, 0, 0); \
;     __builtin_amdgcn_s_setprio(0); } while (0)
; #define WAIT_V(n) asm volatile("s_waitcnt vmcnt(" #n ")" ::: "memory")
; #define WAIT_L(n) asm volatile("s_waitcnt lgkmcnt(" #n ")" ::: "memory")
; #define BAR __builtin_amdgcn_s_barrier()
; #define SCHED __builtin_amdgcn_sched_barrier(0)
; template <int EPI>
; __device__ __forceinline__ void gemm_tile(const GemmArgs& g, int brow, int bcol, int parity, bool first, bool nvalid, int nbrow, int nbcol) {
;     ...
;     STAGE_B(SB(1, 1), bcol + HALF, t + 3);
;     WAIT_V(6); BAR; MMA(1, 1, At, B1); BAR; SCHED;
;   }
;   { LDB(B0, 0, 0); LDA(At, 0, 0); STAGE_A(SA(1, 1), brow + HALF, nt - 1);
;     BAR; WAIT_L(0); MMA(0, 0, At, B0); BAR;
	s_waitcnt lgkmcnt(0)
	s_setprio 1
	s_waitcnt lgkmcnt(0)
	v_mfma_f32_16x16x32_bf16 v[62:65], v[164:167], v[180:183], v[62:65]
	v_mfma_f32_16x16x32_bf16 v[58:61], v[172:175], v[180:183], v[58:61]
	v_mfma_f32_16x16x32_bf16 v[54:57], v[164:167], v[188:191], v[54:57]
	v_mfma_f32_16x16x32_bf16 v[50:53], v[172:175], v[188:191], v[50:53]
	v_mfma_f32_16x16x32_bf16 v[46:49], v[164:167], v[196:199], v[46:49]
	v_mfma_f32_16x16x32_bf16 v[42:45], v[172:175], v[196:199], v[42:45]
	v_mfma_f32_16x16x32_bf16 v[38:41], v[164:167], v[206:209], v[38:41]
	v_mfma_f32_16x16x32_bf16 v[34:37], v[172:175], v[206:209], v[34:37]
	v_mfma_f32_16x16x32_bf16 v[62:65], v[168:171], v[184:187], v[62:65]
	v_mfma_f32_16x16x32_bf16 v[58:61], v[176:179], v[184:187], v[58:61]
	v_mfma_f32_16x16x32_bf16 v[54:57], v[168:171], v[192:195], v[54:57]
	v_mfma_f32_16x16x32_bf16 v[50:53], v[176:179], v[192:195], v[50:53]
	v_mfma_f32_16x16x32_bf16 v[46:49], v[168:171], v[202:205], v[46:49]
	v_mfma_f32_16x16x32_bf16 v[42:45], v[176:179], v[202:205], v[42:45]
	v_mfma_f32_16x16x32_bf16 v[38:41], v[168:171], v[216:219], v[38:41]
	v_mfma_f32_16x16x32_bf16 v[34:37], v[176:179], v[216:219], v[34:37]
	s_setprio 0
	s_barrier
	v_readfirstlane_b32 s2, v155
	v_lshl_add_u64 v[164:165], v[212:213], 0, s[60:61]
	s_mov_b32 m0, s2
	v_readfirstlane_b32 s2, v156
	global_load_lds_dwordx4 v[164:165], off
	v_lshl_add_u64 v[164:165], v[212:213], 0, s[94:95]
	s_mov_b32 m0, s2
	s_nop 0
	global_load_lds_dwordx4 v[164:165], off
	s_waitcnt vmcnt(6)
	s_barrier
	s_setprio 1
	v_mfma_f32_16x16x32_bf16 v[30:33], v[228:231], v[180:183], v[30:33]
	v_mfma_f32_16x16x32_bf16 v[26:29], v[236:239], v[180:183], v[26:29]
	v_mfma_f32_16x16x32_bf16 v[22:25], v[228:231], v[188:191], v[22:25]
	v_mfma_f32_16x16x32_bf16 v[18:21], v[236:239], v[188:191], v[18:21]
	v_mfma_f32_16x16x32_bf16 v[14:17], v[228:231], v[196:199], v[14:17]
	v_mfma_f32_16x16x32_bf16 v[10:13], v[236:239], v[196:199], v[10:13]
	v_mfma_f32_16x16x32_bf16 v[6:9], v[228:231], v[206:209], v[6:9]
	v_mfma_f32_16x16x32_bf16 v[2:5], v[236:239], v[206:209], v[2:5]
	v_mfma_f32_16x16x32_bf16 v[30:33], v[232:235], v[184:187], v[30:33]
	v_mfma_f32_16x16x32_bf16 v[26:29], v[240:243], v[184:187], v[26:29]
	v_mfma_f32_16x16x32_bf16 v[22:25], v[232:235], v[192:195], v[22:25]
	v_mfma_f32_16x16x32_bf16 v[18:21], v[240:243], v[192:195], v[18:21]
	v_mfma_f32_16x16x32_bf16 v[14:17], v[232:235], v[202:205], v[14:17]
	v_mfma_f32_16x16x32_bf16 v[10:13], v[240:243], v[202:205], v[10:13]
	v_mfma_f32_16x16x32_bf16 v[6:9], v[232:235], v[216:219], v[6:9]
	v_mfma_f32_16x16x32_bf16 v[2:5], v[240:243], v[216:219], v[2:5]
	s_setprio 0
	s_barrier
	s_add_i32 s23, s23, 2
	s_add_u32 s12, s12, 0x100
	s_addc_u32 s13, s13, 0
	s_add_u32 s0, s0, 0x100
	s_addc_u32 s1, s1, 0
	s_cmp_lt_u32 s23, 12
	s_cbranch_scc1 .LBB0_640
	s_or_b32 s0, s40, 0x80
	s_ashr_i32 s1, s0, 31
	s_lshl_b64 s[0:1], s[0:1], 11
	s_add_u32 s0, s80, s0
	s_addc_u32 s1, s81, s1
	v_lshl_add_u64 v[130:131], s[0:1], 0, v[0:1]
	s_mov_b64 s[0:1], 0x780
	ds_read_b128 v[150:153], v157
	ds_read_b128 v[164:167], v157 offset:1024
	ds_read_b128 v[168:171], v157 offset:2048
	ds_read_b128 v[172:175], v157 offset:3072
	ds_read_b128 v[176:179], v147
	ds_read_b128 v[180:183], v147 offset:1024
	ds_read_b128 v[184:187], v146
	ds_read_b128 v[188:191], v146 offset:1024
	ds_read_b128 v[192:195], v145
	ds_read_b128 v[196:199], v145 offset:1024
	ds_read_b128 v[202:205], v144
	ds_read_b128 v[206:209], v144 offset:1024
	v_lshl_add_u64 v[156:157], v[130:131], 0, s[0:1]
	v_readfirstlane_b32 s0, v161
	s_mov_b32 m0, s0
	s_mov_b64 s[0:1], 0x20780
	v_lshl_add_u64 v[130:131], v[130:131], 0, s[0:1]
	v_readfirstlane_b32 s0, v162
	global_load_lds_dwordx4 v[156:157], off
	s_mov_b32 m0, s0
	s_nop 0
	global_load_lds_dwordx4 v[130:131], off
	s_barrier
	s_waitcnt lgkmcnt(0)
	s_setprio 1
	s_waitcnt lgkmcnt(0)
	v_mfma_f32_16x16x32_bf16 v[126:129], v[150:153], v[176:179], v[126:129]
	v_mfma_f32_16x16x32_bf16 v[118:121], v[150:153], v[184:187], v[118:121]
	v_mfma_f32_16x16x32_bf16 v[110:113], v[150:153], v[192:195], v[110:113]
	v_mfma_f32_16x16x32_bf16 v[102:105], v[150:153], v[202:205], v[102:105]
	v_mfma_f32_16x16x32_bf16 v[126:129], v[164:167], v[180:183], v[126:129]
	v_mfma_f32_16x16x32_bf16 v[122:125], v[168:171], v[176:179], v[122:125]
	v_mfma_f32_16x16x32_bf16 v[118:121], v[164:167], v[188:191], v[118:121]
	v_mfma_f32_16x16x32_bf16 v[114:117], v[168:171], v[184:187], v[114:117]
	v_mfma_f32_16x16x32_bf16 v[110:113], v[164:167], v[196:199], v[110:113]
	v_mfma_f32_16x16x32_bf16 v[106:109], v[168:171], v[192:195], v[106:109]
	v_mfma_f32_16x16x32_bf16 v[102:105], v[164:167], v[206:209], v[102:105]
	v_mfma_f32_16x16x32_bf16 v[98:101], v[168:171], v[202:205], v[98:101]
	v_mfma_f32_16x16x32_bf16 v[216:219], v[172:175], v[180:183], v[122:125]
	v_mfma_f32_16x16x32_bf16 v[228:231], v[172:175], v[188:191], v[114:117]
	v_mfma_f32_16x16x32_bf16 v[232:235], v[172:175], v[196:199], v[106:109]
	v_mfma_f32_16x16x32_bf16 v[236:239], v[172:175], v[206:209], v[98:101]
	s_setprio 0
	s_barrier
	s_nop 1
	ds_read_b128 v[98:101], v154
	ds_read_b128 v[106:109], v154 offset:1024
	ds_read_b128 v[114:117], v154 offset:2048
	ds_read_b128 v[122:125], v154 offset:3072
	s_barrier
; #define LDA(dst, b, h) for (int m = 0; m < 4; ++m) for (int k = 0; k < 2; ++k) \
;     dst[m][k] = *reinterpret_cast<const bf16x8*>((char*)SA(b, h) + lds_byte(wr * 64 + m * 16 + fr, k * 32 + fq * 8))
; #define LDB(dst, b, h) for (int n = 0; n < 2; ++n) for (int k = 0; k < 2; ++k) \
;     dst[n][k] = *reinterpret_cast<const bf16x8*>((char*)SB(b, h) + lds_byte(wc * 32 + n * 16 + fr, k * 32 + fq * 8))
; #define MMA(ai, bj, At_, Bt_) do { __builtin_amdgcn_s_setprio(1); \
;     for (int m = 0; m < 4; ++m) for (int n = 0; n < 2; ++n) for (int k = 0; k < 2; ++k) \
;       acc[ai][bj][m][n] = __builtin_amdgcn_mfma_f32_16x16x32_bf16(At_[m][k], Bt_[n][k], acc[ai][bj][m][n], 0, 0, 0); \
;     __builtin_amdgcn_s_setprio(0); } while (0)
; #define WAIT_V(n) asm volatile("s_waitcnt vmcnt(" #n ")" ::: "memory")
; #define WAIT_L(n) asm volatile("s_waitcnt lgkmcnt(" #n ")" ::: "memory")
; #define BAR __builtin_amdgcn_s_barrier()
; #define SCHED __builtin_amdgcn_sched_barrier(0)
; template <int EPI>
; __device__ __forceinline__ void gemm_tile(const GemmArgs& g, int brow, int bcol, int parity, bool first, bool nvalid, int nbrow, int nbcol) {
;     ...
;   { LDB(B0, 0, 0); LDA(At, 0, 0); STAGE_A(SA(1, 1), brow + HALF, nt - 1);
;     BAR; WAIT_L(0); MMA(0, 0, At, B0); BAR;
;     LDB(B1, 0, 1); BAR; WAIT_L(0); MMA(0, 1, At, B1); BAR; SCHED;
;     LDA(At, 0, 1); WAIT_V(4); BAR; WAIT_L(0); MMA(1, 0, At, B0); MMA(1, 1, At, B1); BAR; }
;   { LDB(B0, 1, 0); LDA(At, 1, 0); WAIT_V(2); BAR; WAIT_L(0); MMA(0, 0, At, B0); BAR;
;     LDB(B1, 1, 1); WAIT_V(0); BAR; WAIT_L(0); MMA(0, 1, At, B1); BAR; SCHED;
	s_waitcnt lgkmcnt(0)
	s_setprio 1
	s_waitcnt lgkmcnt(0)
	v_mfma_f32_16x16x32_bf16 v[94:97], v[98:101], v[176:179], v[94:97]
	v_mfma_f32_16x16x32_bf16 v[86:89], v[98:101], v[184:187], v[86:89]
	v_mfma_f32_16x16x32_bf16 v[78:81], v[98:101], v[192:195], v[78:81]
	v_mfma_f32_16x16x32_bf16 v[70:73], v[98:101], v[202:205], v[70:73]
	v_mfma_f32_16x16x32_bf16 v[94:97], v[106:109], v[180:183], v[94:97]
	v_mfma_f32_16x16x32_bf16 v[90:93], v[114:117], v[176:179], v[90:93]
	v_mfma_f32_16x16x32_bf16 v[86:89], v[106:109], v[188:191], v[86:89]
	v_mfma_f32_16x16x32_bf16 v[82:85], v[114:117], v[184:187], v[82:85]
	v_mfma_f32_16x16x32_bf16 v[78:81], v[106:109], v[196:199], v[78:81]
	v_mfma_f32_16x16x32_bf16 v[74:77], v[114:117], v[192:195], v[74:77]
	v_mfma_f32_16x16x32_bf16 v[70:73], v[106:109], v[206:209], v[70:73]
	v_mfma_f32_16x16x32_bf16 v[66:69], v[114:117], v[202:205], v[66:69]
	v_mfma_f32_16x16x32_bf16 v[154:157], v[122:125], v[180:183], v[90:93]
	v_mfma_f32_16x16x32_bf16 v[176:179], v[122:125], v[188:191], v[82:85]
	v_mfma_f32_16x16x32_bf16 v[180:183], v[122:125], v[196:199], v[74:77]
	v_mfma_f32_16x16x32_bf16 v[184:187], v[122:125], v[206:209], v[66:69]
	s_setprio 0
	s_barrier
	s_nop 1
	ds_read_b128 v[66:69], v147 offset:16384
	ds_read_b128 v[74:77], v147 offset:17408
	ds_read_b128 v[82:85], v146 offset:16384
	ds_read_b128 v[90:93], v146 offset:17408
	ds_read_b128 v[188:191], v145 offset:16384
	ds_read_b128 v[192:195], v145 offset:17408
	ds_read_b128 v[196:199], v144 offset:16384
	ds_read_b128 v[202:205], v144 offset:17408
	s_waitcnt vmcnt(4)
	s_barrier
	s_waitcnt lgkmcnt(0)
	s_setprio 1
	s_waitcnt lgkmcnt(0)
	v_mfma_f32_16x16x32_bf16 v[62:65], v[150:153], v[66:69], v[62:65]
	v_mfma_f32_16x16x32_bf16 v[54:57], v[150:153], v[82:85], v[54:57]
	v_mfma_f32_16x16x32_bf16 v[46:49], v[150:153], v[188:191], v[46:49]
	v_mfma_f32_16x16x32_bf16 v[38:41], v[150:153], v[196:199], v[38:41]
	v_mfma_f32_16x16x32_bf16 v[62:65], v[164:167], v[74:77], v[62:65]
	v_mfma_f32_16x16x32_bf16 v[58:61], v[168:171], v[66:69], v[58:61]
	v_mfma_f32_16x16x32_bf16 v[54:57], v[164:167], v[90:93], v[54:57]
	v_mfma_f32_16x16x32_bf16 v[50:53], v[168:171], v[82:85], v[50:53]
	v_mfma_f32_16x16x32_bf16 v[46:49], v[164:167], v[192:195], v[46:49]
	v_mfma_f32_16x16x32_bf16 v[42:45], v[168:171], v[188:191], v[42:45]
	v_mfma_f32_16x16x32_bf16 v[38:41], v[164:167], v[202:205], v[38:41]
	v_mfma_f32_16x16x32_bf16 v[34:37], v[168:171], v[196:199], v[34:37]
	v_mfma_f32_16x16x32_bf16 v[206:209], v[172:175], v[74:77], v[58:61]
	v_mfma_f32_16x16x32_bf16 v[240:243], v[172:175], v[90:93], v[50:53]
	v_mfma_f32_16x16x32_bf16 v[244:247], v[172:175], v[192:195], v[42:45]
	v_mfma_f32_16x16x32_bf16 v[150:153], v[172:175], v[202:205], v[34:37]
	s_setprio 0
	s_setprio 1
	v_mfma_f32_16x16x32_bf16 v[30:33], v[98:101], v[66:69], v[30:33]
	v_mfma_f32_16x16x32_bf16 v[22:25], v[98:101], v[82:85], v[22:25]
	v_mfma_f32_16x16x32_bf16 v[14:17], v[98:101], v[188:191], v[14:17]
	v_mfma_f32_16x16x32_bf16 v[6:9], v[98:101], v[196:199], v[6:9]
	v_mfma_f32_16x16x32_bf16 v[30:33], v[106:109], v[74:77], v[30:33]
	v_mfma_f32_16x16x32_bf16 v[26:29], v[114:117], v[66:69], v[26:29]
	v_mfma_f32_16x16x32_bf16 v[22:25], v[106:109], v[90:93], v[22:25]
	v_mfma_f32_16x16x32_bf16 v[18:21], v[114:117], v[82:85], v[18:21]
	v_mfma_f32_16x16x32_bf16 v[14:17], v[106:109], v[192:195], v[14:17]
	v_mfma_f32_16x16x32_bf16 v[10:13], v[114:117], v[188:191], v[10:13]
	v_mfma_f32_16x16x32_bf16 v[6:9], v[106:109], v[202:205], v[6:9]
	v_mfma_f32_16x16x32_bf16 v[2:5], v[114:117], v[196:199], v[2:5]
	v_mfma_f32_16x16x32_bf16 v[162:165], v[122:125], v[74:77], v[26:29]
	v_mfma_f32_16x16x32_bf16 v[166:169], v[122:125], v[90:93], v[18:21]
	v_mfma_f32_16x16x32_bf16 v[170:173], v[122:125], v[192:195], v[10:13]
	v_mfma_f32_16x16x32_bf16 v[188:191], v[122:125], v[202:205], v[2:5]
	s_setprio 0
	s_barrier
	s_nop 1
	ds_read_b128 v[2:5], v149
	ds_read_b128 v[10:13], v149 offset:1024
	ds_read_b128 v[18:21], v149 offset:2048
	ds_read_b128 v[26:29], v149 offset:3072
	ds_read_b128 v[34:37], v147 offset:32768
	ds_read_b128 v[42:45], v147 offset:33792
	ds_read_b128 v[50:53], v146 offset:32768
	ds_read_b128 v[58:61], v146 offset:33792
	ds_read_b128 v[66:69], v145 offset:32768
	ds_read_b128 v[192:195], v145 offset:33792
	ds_read_b128 v[196:199], v144 offset:32768
	ds_read_b128 v[202:205], v144 offset:33792
	s_waitcnt vmcnt(2)
	s_barrier
; #define LDA(dst, b, h) for (int m = 0; m < 4; ++m) for (int k = 0; k < 2; ++k) \
;     dst[m][k] = *reinterpret_cast<const bf16x8*>((char*)SA(b, h) + lds_byte(wr * 64 + m * 16 + fr, k * 32 + fq * 8))
; #define LDB(dst, b, h) for (int n = 0; n < 2; ++n) for (int k = 0; k < 2; ++k) \
;     dst[n][k] = *reinterpret_cast<const bf16x8*>((char*)SB(b, h) + lds_byte(wc * 32 + n * 16 + fr, k * 32 + fq * 8))
; #define MMA(ai, bj, At_, Bt_) do { __builtin_amdgcn_s_setprio(1); \
;     for (int m = 0; m < 4; ++m) for (int n = 0; n < 2; ++n) for (int k = 0; k < 2; ++k) \
;       acc[ai][bj][m][n] = __builtin_amdgcn_mfma_f32_16x16x32_bf16(At_[m][k], Bt_[n][k], acc[ai][bj][m][n], 0, 0, 0); \
;     __builtin_amdgcn_s_setprio(0); } while (0)
; #define WAIT_V(n) asm volatile("s_waitcnt vmcnt(" #n ")" ::: "memory")
; #define WAIT_L(n) asm volatile("s_waitcnt lgkmcnt(" #n ")" ::: "memory")
; #define BAR __builtin_amdgcn_s_barrier()
; #define SCHED __builtin_amdgcn_sched_barrier(0)
; template <int EPI>
; __device__ __forceinline__ void gemm_tile(const GemmArgs& g, int brow, int bcol, int parity, bool first, bool nvalid, int nbrow, int nbcol) {
;     ...
;   { LDB(B0, 1, 0); LDA(At, 1, 0); WAIT_V(2); BAR; WAIT_L(0); MMA(0, 0, At, B0); BAR;
;     LDB(B1, 1, 1); WAIT_V(0); BAR; WAIT_L(0); MMA(0, 1, At, B1); BAR; SCHED;
;     LDA(At, 1, 1); BAR; WAIT_L(0); MMA(1, 0, At, B0); MMA(1, 1, At, B1); BAR; }
;   if (wr == 0) BAR;
	s_waitcnt lgkmcnt(0)
	s_setprio 1
	s_waitcnt lgkmcnt(0)
	v_mfma_f32_16x16x32_bf16 v[74:77], v[2:5], v[34:37], v[126:129]
	v_mfma_f32_16x16x32_bf16 v[122:125], v[10:13], v[42:45], v[74:77]
	v_mfma_f32_16x16x32_bf16 v[74:77], v[18:21], v[34:37], v[216:219]
	v_mfma_f32_16x16x32_bf16 v[126:129], v[26:29], v[42:45], v[74:77]
	v_mfma_f32_16x16x32_bf16 v[74:77], v[2:5], v[50:53], v[118:121]
	v_mfma_f32_16x16x32_bf16 v[114:117], v[10:13], v[58:61], v[74:77]
	v_mfma_f32_16x16x32_bf16 v[74:77], v[18:21], v[50:53], v[228:231]
	v_mfma_f32_16x16x32_bf16 v[118:121], v[26:29], v[58:61], v[74:77]
	v_mfma_f32_16x16x32_bf16 v[74:77], v[2:5], v[66:69], v[110:113]
	v_mfma_f32_16x16x32_bf16 v[106:109], v[10:13], v[192:195], v[74:77]
	v_mfma_f32_16x16x32_bf16 v[74:77], v[18:21], v[66:69], v[232:235]
	v_mfma_f32_16x16x32_bf16 v[110:113], v[26:29], v[192:195], v[74:77]
	v_mfma_f32_16x16x32_bf16 v[74:77], v[2:5], v[196:199], v[102:105]
	v_mfma_f32_16x16x32_bf16 v[98:101], v[10:13], v[202:205], v[74:77]
	v_mfma_f32_16x16x32_bf16 v[74:77], v[18:21], v[196:199], v[236:239]
	v_mfma_f32_16x16x32_bf16 v[102:105], v[26:29], v[202:205], v[74:77]
	s_setprio 0
	s_barrier
	ds_read_b128 v[216:219], v148
	ds_read_b128 v[228:231], v148 offset:1024
	ds_read_b128 v[232:235], v148 offset:2048
	ds_read_b128 v[236:239], v148 offset:3072
	s_waitcnt vmcnt(0)
	s_barrier
	s_waitcnt lgkmcnt(0)
	s_setprio 1
	s_waitcnt lgkmcnt(0)
	v_mfma_f32_16x16x32_bf16 v[74:77], v[216:219], v[34:37], v[94:97]
	v_mfma_f32_16x16x32_bf16 v[34:37], v[232:235], v[34:37], v[154:157]
	v_mfma_f32_16x16x32_bf16 v[94:97], v[236:239], v[42:45], v[34:37]
	v_mfma_f32_16x16x32_bf16 v[34:37], v[216:219], v[50:53], v[86:89]
	v_mfma_f32_16x16x32_bf16 v[82:85], v[228:231], v[58:61], v[34:37]
	v_mfma_f32_16x16x32_bf16 v[34:37], v[232:235], v[50:53], v[176:179]
	v_mfma_f32_16x16x32_bf16 v[86:89], v[236:239], v[58:61], v[34:37]
	v_mfma_f32_16x16x32_bf16 v[34:37], v[216:219], v[66:69], v[78:81]
	v_mfma_f32_16x16x32_bf16 v[90:93], v[228:231], v[42:45], v[74:77]
	v_mfma_f32_16x16x32_bf16 v[74:77], v[228:231], v[192:195], v[34:37]
	v_mfma_f32_16x16x32_bf16 v[34:37], v[232:235], v[66:69], v[180:183]
	v_mfma_f32_16x16x32_bf16 v[78:81], v[236:239], v[192:195], v[34:37]
	v_mfma_f32_16x16x32_bf16 v[34:37], v[216:219], v[196:199], v[70:73]
	v_mfma_f32_16x16x32_bf16 v[66:69], v[228:231], v[202:205], v[34:37]
	v_mfma_f32_16x16x32_bf16 v[34:37], v[232:235], v[196:199], v[184:187]
	v_mfma_f32_16x16x32_bf16 v[70:73], v[236:239], v[202:205], v[34:37]
	s_setprio 0
	s_barrier
	ds_read_b128 v[154:157], v147 offset:49152
	ds_read_b128 v[174:177], v147 offset:50176
	ds_read_b128 v[178:181], v146 offset:49152
	ds_read_b128 v[146:149], v146 offset:50176
	ds_read_b128 v[182:185], v145 offset:49152
	ds_read_b128 v[192:195], v145 offset:50176
	ds_read_b128 v[196:199], v144 offset:49152
	ds_read_b128 v[202:205], v144 offset:50176
	s_barrier
	s_waitcnt lgkmcnt(0)
	s_setprio 1
	s_waitcnt lgkmcnt(0)
	v_mfma_f32_16x16x32_bf16 v[34:37], v[2:5], v[154:157], v[62:65]
	v_mfma_f32_16x16x32_bf16 v[58:61], v[10:13], v[174:177], v[34:37]
	v_mfma_f32_16x16x32_bf16 v[34:37], v[18:21], v[154:157], v[206:209]
	v_mfma_f32_16x16x32_bf16 v[62:65], v[26:29], v[174:177], v[34:37]
	v_mfma_f32_16x16x32_bf16 v[34:37], v[2:5], v[178:181], v[54:57]
	v_mfma_f32_16x16x32_bf16 v[50:53], v[10:13], v[146:149], v[34:37]
	v_mfma_f32_16x16x32_bf16 v[34:37], v[18:21], v[178:181], v[240:243]
	v_mfma_f32_16x16x32_bf16 v[54:57], v[26:29], v[146:149], v[34:37]
	v_mfma_f32_16x16x32_bf16 v[34:37], v[2:5], v[182:185], v[46:49]
	v_mfma_f32_16x16x32_bf16 v[42:45], v[10:13], v[192:195], v[34:37]
	v_mfma_f32_16x16x32_bf16 v[34:37], v[18:21], v[182:185], v[244:247]
	v_mfma_f32_16x16x32_bf16 v[2:5], v[2:5], v[196:199], v[38:41]
	v_mfma_f32_16x16x32_bf16 v[46:49], v[26:29], v[192:195], v[34:37]
	v_mfma_f32_16x16x32_bf16 v[34:37], v[10:13], v[202:205], v[2:5]
	v_mfma_f32_16x16x32_bf16 v[2:5], v[18:21], v[196:199], v[150:153]
	v_mfma_f32_16x16x32_bf16 v[38:41], v[26:29], v[202:205], v[2:5]
	s_setprio 0
	s_setprio 1
	v_mfma_f32_16x16x32_bf16 v[2:5], v[216:219], v[154:157], v[30:33]
	v_mfma_f32_16x16x32_bf16 v[26:29], v[228:231], v[174:177], v[2:5]
	v_mfma_f32_16x16x32_bf16 v[2:5], v[232:235], v[154:157], v[162:165]
	v_mfma_f32_16x16x32_bf16 v[30:33], v[236:239], v[174:177], v[2:5]
	v_mfma_f32_16x16x32_bf16 v[2:5], v[216:219], v[178:181], v[22:25]
	v_mfma_f32_16x16x32_bf16 v[18:21], v[228:231], v[146:149], v[2:5]
	v_mfma_f32_16x16x32_bf16 v[2:5], v[232:235], v[178:181], v[166:169]
	v_mfma_f32_16x16x32_bf16 v[22:25], v[236:239], v[146:149], v[2:5]
	v_mfma_f32_16x16x32_bf16 v[2:5], v[216:219], v[182:185], v[14:17]
	v_mfma_f32_16x16x32_bf16 v[10:13], v[228:231], v[192:195], v[2:5]
	v_mfma_f32_16x16x32_bf16 v[2:5], v[232:235], v[182:185], v[170:173]
	v_mfma_f32_16x16x32_bf16 v[14:17], v[236:239], v[192:195], v[2:5]
	v_mfma_f32_16x16x32_bf16 v[2:5], v[216:219], v[196:199], v[6:9]
	v_mfma_f32_16x16x32_bf16 v[6:9], v[232:235], v[196:199], v[188:191]
	v_mfma_f32_16x16x32_bf16 v[2:5], v[228:231], v[202:205], v[2:5]
	v_mfma_f32_16x16x32_bf16 v[6:9], v[236:239], v[202:205], v[6:9]
	s_setprio 0
	s_movk_i32 s0, 0x100
	v_cmp_gt_u32_e32 vcc, s0, v138
	s_barrier
	s_and_saveexec_b64 s[0:1], vcc
	s_cbranch_execz .LBB0_643
	s_barrier
